# removed the per-phase s_setprio 1/0 flips in the four GEMM main loops (timing only)
# speedup vs baseline: 1.0276x; 1.0090x over previous
; #define PG8_STAGE(bufoff, gbase, voff) do { _Pragma("unroll") for (int _i = 0; _i < 2; ++_i) \
;         __builtin_amdgcn_global_load_lds((const unsigned*)((const char*)(gbase) + (voff)[_i]), (LAS unsigned*)(lds + (bufoff) + ldsw + _i * 8192), 16, 0, 0); } while (0)
; #define PG8_LDA(dst, b, h) do { _Pragma("unroll") for (int m = 0; m < 4; ++m) _Pragma("unroll") for (int k = 0; k < 2; ++k) dst[m][k] = *(const LAS bf16x8*)(lds + PG8_SA(b, h) + aoff + m * 2048 + k * 1024); } while (0)
; #define PG8_LDB(dst, b, h) do { _Pragma("unroll") for (int n = 0; n < 2; ++n) _Pragma("unroll") for (int k = 0; k < 2; ++k) dst[n][k] = *(const LAS bf16x8*)(lds + PG8_SB(b, h) + boff + n * 2048 + k * 1024); } while (0)
; #define PG8_MMA(ai, bj, At, Bt) do { __builtin_amdgcn_s_setprio(1); _Pragma("unroll") for (int m = 0; m < 4; ++m) _Pragma("unroll") for (int n = 0; n < 2; ++n) _Pragma("unroll") for (int k = 0; k < 2; ++k) \
;         acc[ai][bj][m][n] = __builtin_amdgcn_mfma_f32_16x16x32_bf16(Bt[n][k], At[m][k], acc[ai][bj][m][n], 0, 0, 0); __builtin_amdgcn_s_setprio(0); } while (0)
; #define PG8_WAIT_V(n) asm volatile("s_waitcnt vmcnt(" #n ")" ::: "memory")
; #define PG8_WAIT_L(n) asm volatile("s_waitcnt lgkmcnt(" #n ")" ::: "memory")
; #define PG8_BAR __builtin_amdgcn_s_barrier()
; #define PG8_SCHED __builtin_amdgcn_sched_barrier(0)
; template <class Epi, class Sched>
; __device__ __forceinline__ void gemm_phase(LAS unsigned char* lds, const Gemm g, const Sched& S, const Epi& E) {
;     ...
;             PG8_LDB(B0, 0, 0); PG8_SCHED; PG8_LDA(At, 0, 0); PG8_STAGE(PG8_SA(1, 1), a1 + hstep, voffA);
;             PG8_WAIT_L(8); PG8_BAR; PG8_WAIT_L(0); PG8_MMA(0, 0, At, B0); PG8_BAR; PG8_SCHED;
;             PG8_LDB(B1, 0, 1); PG8_STAGE(PG8_SB(0, 0), b2, voffB);
;             PG8_BAR; PG8_WAIT_L(0); PG8_MMA(0, 1, At, B1); PG8_BAR;
;             PG8_LDA(At, 0, 1); PG8_STAGE(PG8_SA(0, 0), a2, voffA);
;             PG8_BAR; PG8_WAIT_L(0); PG8_MMA(1, 0, At, B0); PG8_BAR; PG8_SCHED;
;             PG8_STAGE(PG8_SB(0, 1), b2 + hstep, voffB);
;             PG8_WAIT_V(6); PG8_BAR; PG8_MMA(1, 1, At, B1); PG8_BAR;
.LBB0_342:
	s_nop 0
	v_add_u32_e32 v158, s42, v147
	ds_read_b128 v[142:145], v158
	ds_read_b128 v[150:153], v158 offset:1024
	ds_read_b128 v[154:157], v158 offset:2048
	ds_read_b128 v[158:161], v158 offset:3072
	s_add_u32 s18, s16, 0xfff80080
	s_addc_u32 s19, s17, -1
	s_cmp_eq_u32 s38, 28
	s_cselect_b32 s21, s11, s19
	s_cselect_b32 s20, s34, s18
	s_cselect_b32 s19, s9, s37
	s_cselect_b32 s18, s35, s36
	v_lshl_add_u64 v[194:195], s[16:17], 0, v[138:139]
	s_add_i32 m0, s24, 0xc000
	ds_read_b128 v[162:165], v149
	ds_read_b128 v[166:169], v149 offset:1024
	ds_read_b128 v[170:173], v149 offset:2048
	ds_read_b128 v[174:177], v149 offset:3072
	ds_read_b128 v[178:181], v149 offset:4096
	ds_read_b128 v[182:185], v149 offset:5120
	ds_read_b128 v[186:189], v149 offset:6144
	ds_read_b128 v[190:193], v149 offset:7168
	global_load_lds_dwordx4 v[194:195], off
	v_lshl_add_u64 v[194:195], s[16:17], 0, v[140:141]
	s_add_i32 m0, s24, 0xe000
	s_nop 0
	global_load_lds_dwordx4 v[194:195], off
	s_waitcnt lgkmcnt(8)
	s_barrier
	s_waitcnt lgkmcnt(0)
	s_waitcnt lgkmcnt(0)
	v_mfma_f32_16x16x32_bf16 v[126:129], v[142:145], v[162:165], v[126:129]
	v_mfma_f32_16x16x32_bf16 v[122:125], v[154:157], v[162:165], v[122:125]
	v_mfma_f32_16x16x32_bf16 v[114:117], v[142:145], v[170:173], v[114:117]
	v_mfma_f32_16x16x32_bf16 v[106:109], v[154:157], v[170:173], v[106:109]
	v_mfma_f32_16x16x32_bf16 v[98:101], v[142:145], v[178:181], v[98:101]
	v_mfma_f32_16x16x32_bf16 v[90:93], v[154:157], v[178:181], v[90:93]
	v_mfma_f32_16x16x32_bf16 v[82:85], v[142:145], v[186:189], v[82:85]
	v_mfma_f32_16x16x32_bf16 v[74:77], v[154:157], v[186:189], v[74:77]
	v_mfma_f32_16x16x32_bf16 v[126:129], v[150:153], v[166:169], v[126:129]
	v_mfma_f32_16x16x32_bf16 v[122:125], v[158:161], v[166:169], v[122:125]
	v_mfma_f32_16x16x32_bf16 v[114:117], v[150:153], v[174:177], v[114:117]
	v_mfma_f32_16x16x32_bf16 v[106:109], v[158:161], v[174:177], v[106:109]
	v_mfma_f32_16x16x32_bf16 v[98:101], v[150:153], v[182:185], v[98:101]
	v_mfma_f32_16x16x32_bf16 v[90:93], v[158:161], v[182:185], v[90:93]
	v_mfma_f32_16x16x32_bf16 v[82:85], v[150:153], v[190:193], v[82:85]
	v_mfma_f32_16x16x32_bf16 v[74:77], v[158:161], v[190:193], v[74:77]
	s_barrier
	s_add_i32 s39, 0, 0x14000
	s_add_i32 s40, s42, s23
	v_add_u32_e32 v206, s39, v147
	v_lshl_add_u64 v[210:211], s[18:19], 0, v[0:1]
	s_mov_b32 m0, s40
	ds_read_b128 v[194:197], v206
	ds_read_b128 v[198:201], v206 offset:1024
	ds_read_b128 v[202:205], v206 offset:2048
	ds_read_b128 v[206:209], v206 offset:3072
	global_load_lds_dwordx4 v[210:211], off
	v_lshl_add_u64 v[220:221], s[18:19], 0, v[130:131]
	s_add_i32 m0, s40, 0x2000
	s_nop 0
	global_load_lds_dwordx4 v[220:221], off
	s_barrier
	s_waitcnt lgkmcnt(0)
	s_waitcnt lgkmcnt(0)
	v_mfma_f32_16x16x32_bf16 v[118:121], v[194:197], v[162:165], v[118:121]
	v_mfma_f32_16x16x32_bf16 v[110:113], v[202:205], v[162:165], v[110:113]
	v_mfma_f32_16x16x32_bf16 v[102:105], v[194:197], v[170:173], v[102:105]
	v_mfma_f32_16x16x32_bf16 v[94:97], v[202:205], v[170:173], v[94:97]
	v_mfma_f32_16x16x32_bf16 v[86:89], v[194:197], v[178:181], v[86:89]
	v_mfma_f32_16x16x32_bf16 v[78:81], v[202:205], v[178:181], v[78:81]
	v_mfma_f32_16x16x32_bf16 v[70:73], v[194:197], v[186:189], v[70:73]
	v_mfma_f32_16x16x32_bf16 v[66:69], v[202:205], v[186:189], v[66:69]
	v_mfma_f32_16x16x32_bf16 v[118:121], v[198:201], v[166:169], v[118:121]
	v_mfma_f32_16x16x32_bf16 v[110:113], v[206:209], v[166:169], v[110:113]
	v_mfma_f32_16x16x32_bf16 v[102:105], v[198:201], v[174:177], v[102:105]
	v_mfma_f32_16x16x32_bf16 v[94:97], v[206:209], v[174:177], v[94:97]
	v_mfma_f32_16x16x32_bf16 v[86:89], v[198:201], v[182:185], v[86:89]
	v_mfma_f32_16x16x32_bf16 v[78:81], v[206:209], v[182:185], v[78:81]
	v_mfma_f32_16x16x32_bf16 v[70:73], v[198:201], v[190:193], v[70:73]
	v_mfma_f32_16x16x32_bf16 v[66:69], v[206:209], v[190:193], v[66:69]
	s_mov_b32 m0, s24
	v_lshl_add_u64 v[222:223], s[20:21], 0, v[134:135]
	s_barrier
	ds_read_b128 v[162:165], v149 offset:16384
	ds_read_b128 v[166:169], v149 offset:17408
	ds_read_b128 v[170:173], v149 offset:18432
	ds_read_b128 v[174:177], v149 offset:19456
	ds_read_b128 v[178:181], v149 offset:20480
	ds_read_b128 v[182:185], v149 offset:21504
	ds_read_b128 v[186:189], v149 offset:22528
	ds_read_b128 v[190:193], v149 offset:23552
	global_load_lds_dwordx4 v[222:223], off
	v_lshl_add_u64 v[234:235], s[20:21], 0, v[132:133]
	s_mov_b32 m0, s25
	s_nop 0
	global_load_lds_dwordx4 v[234:235], off
	s_barrier
	s_waitcnt lgkmcnt(0)
	s_waitcnt lgkmcnt(0)
	v_mfma_f32_16x16x32_bf16 v[62:65], v[142:145], v[162:165], v[62:65]
	v_mfma_f32_16x16x32_bf16 v[58:61], v[154:157], v[162:165], v[58:61]
	v_mfma_f32_16x16x32_bf16 v[50:53], v[142:145], v[170:173], v[50:53]
	v_mfma_f32_16x16x32_bf16 v[42:45], v[154:157], v[170:173], v[42:45]
	v_mfma_f32_16x16x32_bf16 v[34:37], v[142:145], v[178:181], v[34:37]
	v_mfma_f32_16x16x32_bf16 v[26:29], v[154:157], v[178:181], v[26:29]
	v_mfma_f32_16x16x32_bf16 v[18:21], v[142:145], v[186:189], v[18:21]
	v_mfma_f32_16x16x32_bf16 v[10:13], v[154:157], v[186:189], v[10:13]
	v_mfma_f32_16x16x32_bf16 v[62:65], v[150:153], v[166:169], v[62:65]
	v_mfma_f32_16x16x32_bf16 v[58:61], v[158:161], v[166:169], v[58:61]
	v_mfma_f32_16x16x32_bf16 v[50:53], v[150:153], v[174:177], v[50:53]
	v_mfma_f32_16x16x32_bf16 v[42:45], v[158:161], v[174:177], v[42:45]
	v_mfma_f32_16x16x32_bf16 v[34:37], v[150:153], v[182:185], v[34:37]
	v_mfma_f32_16x16x32_bf16 v[26:29], v[158:161], v[182:185], v[26:29]
	v_mfma_f32_16x16x32_bf16 v[18:21], v[150:153], v[190:193], v[18:21]
	v_mfma_f32_16x16x32_bf16 v[10:13], v[158:161], v[190:193], v[10:13]
	s_barrier
; #define PG8_STAGE(bufoff, gbase, voff) do { _Pragma("unroll") for (int _i = 0; _i < 2; ++_i) \
;         __builtin_amdgcn_global_load_lds((const unsigned*)((const char*)(gbase) + (voff)[_i]), (LAS unsigned*)(lds + (bufoff) + ldsw + _i * 8192), 16, 0, 0); } while (0)
; #define PG8_LDA(dst, b, h) do { _Pragma("unroll") for (int m = 0; m < 4; ++m) _Pragma("unroll") for (int k = 0; k < 2; ++k) dst[m][k] = *(const LAS bf16x8*)(lds + PG8_SA(b, h) + aoff + m * 2048 + k * 1024); } while (0)
; #define PG8_LDB(dst, b, h) do { _Pragma("unroll") for (int n = 0; n < 2; ++n) _Pragma("unroll") for (int k = 0; k < 2; ++k) dst[n][k] = *(const LAS bf16x8*)(lds + PG8_SB(b, h) + boff + n * 2048 + k * 1024); } while (0)
; #define PG8_MMA(ai, bj, At, Bt) do { __builtin_amdgcn_s_setprio(1); _Pragma("unroll") for (int m = 0; m < 4; ++m) _Pragma("unroll") for (int n = 0; n < 2; ++n) _Pragma("unroll") for (int k = 0; k < 2; ++k) \
;         acc[ai][bj][m][n] = __builtin_amdgcn_mfma_f32_16x16x32_bf16(Bt[n][k], At[m][k], acc[ai][bj][m][n], 0, 0, 0); __builtin_amdgcn_s_setprio(0); } while (0)
; #define PG8_WAIT_V(n) asm volatile("s_waitcnt vmcnt(" #n ")" ::: "memory")
; #define PG8_WAIT_L(n) asm volatile("s_waitcnt lgkmcnt(" #n ")" ::: "memory")
; #define PG8_BAR __builtin_amdgcn_s_barrier()
; #define PG8_SCHED __builtin_amdgcn_sched_barrier(0)
; template <class Epi, class Sched>
; __device__ __forceinline__ void gemm_phase(LAS unsigned char* lds, const Gemm g, const Sched& S, const Epi& E) {
;     ...
;             PG8_WAIT_V(6); PG8_BAR; PG8_MMA(1, 1, At, B1); PG8_BAR;
;             PG8_LDB(B0, 1, 0); PG8_SCHED; PG8_LDA(At, 1, 0); PG8_STAGE(PG8_SA(0, 1), a2 + hstep, voffA);
;             PG8_WAIT_L(8); PG8_BAR; PG8_WAIT_L(0); PG8_MMA(0, 0, At, B0); PG8_BAR; PG8_SCHED;
;             PG8_LDB(B1, 1, 1); PG8_STAGE(PG8_SB(1, 0), b3, voffB);
;             PG8_BAR; PG8_WAIT_L(0); PG8_MMA(0, 1, At, B1); PG8_BAR;
;             PG8_LDA(At, 1, 1); PG8_STAGE(PG8_SA(1, 0), a3, voffA);
	s_add_u32 s40, s18, 0x80000
	s_addc_u32 s41, s19, 0
	s_add_i32 s39, s39, s23
	v_lshl_add_u64 v[142:143], s[40:41], 0, v[0:1]
	s_mov_b32 m0, s39
	s_nop 0
	global_load_lds_dwordx4 v[142:143], off
	v_lshl_add_u64 v[142:143], s[40:41], 0, v[130:131]
	s_add_i32 m0, s39, 0x2000
	s_nop 0
	global_load_lds_dwordx4 v[142:143], off
	s_waitcnt vmcnt(6)
	s_barrier
	v_mfma_f32_16x16x32_bf16 v[54:57], v[194:197], v[162:165], v[54:57]
	v_mfma_f32_16x16x32_bf16 v[46:49], v[202:205], v[162:165], v[46:49]
	v_mfma_f32_16x16x32_bf16 v[38:41], v[194:197], v[170:173], v[38:41]
	v_mfma_f32_16x16x32_bf16 v[30:33], v[202:205], v[170:173], v[30:33]
	v_mfma_f32_16x16x32_bf16 v[22:25], v[194:197], v[178:181], v[22:25]
	v_mfma_f32_16x16x32_bf16 v[14:17], v[202:205], v[178:181], v[14:17]
	v_mfma_f32_16x16x32_bf16 v[6:9], v[194:197], v[186:189], v[6:9]
	v_mfma_f32_16x16x32_bf16 v[2:5], v[202:205], v[186:189], v[2:5]
	v_mfma_f32_16x16x32_bf16 v[54:57], v[198:201], v[166:169], v[54:57]
	v_mfma_f32_16x16x32_bf16 v[46:49], v[206:209], v[166:169], v[46:49]
	v_mfma_f32_16x16x32_bf16 v[38:41], v[198:201], v[174:177], v[38:41]
	v_mfma_f32_16x16x32_bf16 v[30:33], v[206:209], v[174:177], v[30:33]
	v_mfma_f32_16x16x32_bf16 v[22:25], v[198:201], v[182:185], v[22:25]
	v_mfma_f32_16x16x32_bf16 v[14:17], v[206:209], v[182:185], v[14:17]
	v_mfma_f32_16x16x32_bf16 v[6:9], v[198:201], v[190:193], v[6:9]
	v_mfma_f32_16x16x32_bf16 v[2:5], v[206:209], v[190:193], v[2:5]
	s_add_i32 s39, 0, 0x18000
	v_add_u32_e32 v158, s39, v147
	s_barrier
	ds_read_b128 v[142:145], v158
	ds_read_b128 v[150:153], v158 offset:1024
	ds_read_b128 v[154:157], v158 offset:2048
	ds_read_b128 v[158:161], v158 offset:3072
	s_add_u32 s20, s20, 0x80000
	s_addc_u32 s21, s21, 0
	s_mov_b32 m0, s26
	v_lshl_add_u64 v[194:195], s[20:21], 0, v[134:135]
	ds_read_b128 v[162:165], v149 offset:32768
	ds_read_b128 v[166:169], v149 offset:33792
	ds_read_b128 v[170:173], v149 offset:34816
	ds_read_b128 v[174:177], v149 offset:35840
	ds_read_b128 v[178:181], v149 offset:36864
	ds_read_b128 v[182:185], v149 offset:37888
	ds_read_b128 v[186:189], v149 offset:38912
	ds_read_b128 v[190:193], v149 offset:39936
	global_load_lds_dwordx4 v[194:195], off
	v_lshl_add_u64 v[194:195], s[20:21], 0, v[132:133]
	s_mov_b32 m0, s27
	s_nop 0
	global_load_lds_dwordx4 v[194:195], off
	s_waitcnt lgkmcnt(8)
	s_barrier
	s_waitcnt lgkmcnt(0)
	s_waitcnt lgkmcnt(0)
	v_mfma_f32_16x16x32_bf16 v[126:129], v[142:145], v[162:165], v[126:129]
	v_mfma_f32_16x16x32_bf16 v[122:125], v[154:157], v[162:165], v[122:125]
	v_mfma_f32_16x16x32_bf16 v[114:117], v[142:145], v[170:173], v[114:117]
	v_mfma_f32_16x16x32_bf16 v[106:109], v[154:157], v[170:173], v[106:109]
	v_mfma_f32_16x16x32_bf16 v[98:101], v[142:145], v[178:181], v[98:101]
	v_mfma_f32_16x16x32_bf16 v[90:93], v[154:157], v[178:181], v[90:93]
	v_mfma_f32_16x16x32_bf16 v[82:85], v[142:145], v[186:189], v[82:85]
	v_mfma_f32_16x16x32_bf16 v[74:77], v[154:157], v[186:189], v[74:77]
	v_mfma_f32_16x16x32_bf16 v[126:129], v[150:153], v[166:169], v[126:129]
	v_mfma_f32_16x16x32_bf16 v[122:125], v[158:161], v[166:169], v[122:125]
	v_mfma_f32_16x16x32_bf16 v[114:117], v[150:153], v[174:177], v[114:117]
	v_mfma_f32_16x16x32_bf16 v[106:109], v[158:161], v[174:177], v[106:109]
	v_mfma_f32_16x16x32_bf16 v[98:101], v[150:153], v[182:185], v[98:101]
	v_mfma_f32_16x16x32_bf16 v[90:93], v[158:161], v[182:185], v[90:93]
	v_mfma_f32_16x16x32_bf16 v[82:85], v[150:153], v[190:193], v[82:85]
	v_mfma_f32_16x16x32_bf16 v[74:77], v[158:161], v[190:193], v[74:77]
	s_barrier
	s_add_i32 s20, 0, 0x1c000
	s_add_i32 s21, s39, s23
	v_add_u32_e32 v206, s20, v147
	v_lshl_add_u64 v[210:211], v[210:211], 0, s[44:45]
	s_mov_b32 m0, s21
	ds_read_b128 v[194:197], v206
	ds_read_b128 v[198:201], v206 offset:1024
	ds_read_b128 v[202:205], v206 offset:2048
	ds_read_b128 v[206:209], v206 offset:3072
	global_load_lds_dwordx4 v[210:211], off
	v_lshl_add_u64 v[210:211], v[220:221], 0, s[44:45]
	s_add_i32 m0, s21, 0x2000
	s_nop 0
	global_load_lds_dwordx4 v[210:211], off
	s_barrier
; #define PG8_STAGE(bufoff, gbase, voff) do { _Pragma("unroll") for (int _i = 0; _i < 2; ++_i) \
;         __builtin_amdgcn_global_load_lds((const unsigned*)((const char*)(gbase) + (voff)[_i]), (LAS unsigned*)(lds + (bufoff) + ldsw + _i * 8192), 16, 0, 0); } while (0)
; #define PG8_LDA(dst, b, h) do { _Pragma("unroll") for (int m = 0; m < 4; ++m) _Pragma("unroll") for (int k = 0; k < 2; ++k) dst[m][k] = *(const LAS bf16x8*)(lds + PG8_SA(b, h) + aoff + m * 2048 + k * 1024); } while (0)
; #define PG8_MMA(ai, bj, At, Bt) do { __builtin_amdgcn_s_setprio(1); _Pragma("unroll") for (int m = 0; m < 4; ++m) _Pragma("unroll") for (int n = 0; n < 2; ++n) _Pragma("unroll") for (int k = 0; k < 2; ++k) \
;         acc[ai][bj][m][n] = __builtin_amdgcn_mfma_f32_16x16x32_bf16(Bt[n][k], At[m][k], acc[ai][bj][m][n], 0, 0, 0); __builtin_amdgcn_s_setprio(0); } while (0)
; #define PG8_WAIT_V(n) asm volatile("s_waitcnt vmcnt(" #n ")" ::: "memory")
; #define PG8_WAIT_L(n) asm volatile("s_waitcnt lgkmcnt(" #n ")" ::: "memory")
; #define PG8_BAR __builtin_amdgcn_s_barrier()
; #define PG8_SCHED __builtin_amdgcn_sched_barrier(0)
; template <class Epi, class Sched>
; __device__ __forceinline__ void gemm_phase(LAS unsigned char* lds, const Gemm g, const Sched& S, const Epi& E) {
;     ...
;             PG8_LDA(At, 1, 1); PG8_STAGE(PG8_SA(1, 0), a3, voffA);
;             PG8_BAR; PG8_WAIT_L(0); PG8_MMA(1, 0, At, B0); PG8_BAR; PG8_SCHED;
;             PG8_STAGE(PG8_SB(1, 1), b3 + hstep, voffB);
;             PG8_WAIT_V(6); PG8_BAR; PG8_MMA(1, 1, At, B1); PG8_BAR;
;     __device__ __forceinline__ void operator()(const f32x4 (&acc)[2][2][4][2], const pg8::Unit& u, int wr, int wc, int fr, int fq) const {
;     ...
;                     if (ACT == 0) { if (u.pn == (C_G / 256) && bj == 0 && wc == 0 && fq < 2) { float* gp = gate + (size_t)row * 16 + 8 * fq; *(f32x4*)gp = v0; *(f32x4*)(gp + 4) = v1; } }
	s_waitcnt lgkmcnt(0)
	s_waitcnt lgkmcnt(0)
	v_mfma_f32_16x16x32_bf16 v[118:121], v[194:197], v[162:165], v[118:121]
	v_mfma_f32_16x16x32_bf16 v[110:113], v[202:205], v[162:165], v[110:113]
	v_mfma_f32_16x16x32_bf16 v[102:105], v[194:197], v[170:173], v[102:105]
	v_mfma_f32_16x16x32_bf16 v[94:97], v[202:205], v[170:173], v[94:97]
	v_mfma_f32_16x16x32_bf16 v[86:89], v[194:197], v[178:181], v[86:89]
	v_mfma_f32_16x16x32_bf16 v[78:81], v[202:205], v[178:181], v[78:81]
	v_mfma_f32_16x16x32_bf16 v[70:73], v[194:197], v[186:189], v[70:73]
	v_mfma_f32_16x16x32_bf16 v[66:69], v[202:205], v[186:189], v[66:69]
	v_mfma_f32_16x16x32_bf16 v[118:121], v[198:201], v[166:169], v[118:121]
	v_mfma_f32_16x16x32_bf16 v[110:113], v[206:209], v[166:169], v[110:113]
	v_mfma_f32_16x16x32_bf16 v[102:105], v[198:201], v[174:177], v[102:105]
	v_mfma_f32_16x16x32_bf16 v[94:97], v[206:209], v[174:177], v[94:97]
	v_mfma_f32_16x16x32_bf16 v[86:89], v[198:201], v[182:185], v[86:89]
	v_mfma_f32_16x16x32_bf16 v[78:81], v[206:209], v[182:185], v[78:81]
	v_mfma_f32_16x16x32_bf16 v[70:73], v[198:201], v[190:193], v[70:73]
	v_mfma_f32_16x16x32_bf16 v[66:69], v[206:209], v[190:193], v[66:69]
	s_mov_b32 m0, s28
	v_lshl_add_u64 v[210:211], v[222:223], 0, s[44:45]
	s_barrier
	ds_read_b128 v[162:165], v149 offset:49152
	ds_read_b128 v[166:169], v149 offset:50176
	ds_read_b128 v[170:173], v149 offset:51200
	ds_read_b128 v[174:177], v149 offset:52224
	ds_read_b128 v[178:181], v149 offset:53248
	ds_read_b128 v[182:185], v149 offset:54272
	ds_read_b128 v[186:189], v149 offset:55296
	ds_read_b128 v[190:193], v149 offset:56320
	global_load_lds_dwordx4 v[210:211], off
	v_lshl_add_u64 v[210:211], v[234:235], 0, s[44:45]
	s_mov_b32 m0, s29
	s_nop 0
	global_load_lds_dwordx4 v[210:211], off
	s_barrier
	s_waitcnt lgkmcnt(0)
	s_waitcnt lgkmcnt(0)
	v_mfma_f32_16x16x32_bf16 v[62:65], v[142:145], v[162:165], v[62:65]
	v_mfma_f32_16x16x32_bf16 v[58:61], v[154:157], v[162:165], v[58:61]
	v_mfma_f32_16x16x32_bf16 v[50:53], v[142:145], v[170:173], v[50:53]
	v_mfma_f32_16x16x32_bf16 v[42:45], v[154:157], v[170:173], v[42:45]
	v_mfma_f32_16x16x32_bf16 v[34:37], v[142:145], v[178:181], v[34:37]
	v_mfma_f32_16x16x32_bf16 v[26:29], v[154:157], v[178:181], v[26:29]
	v_mfma_f32_16x16x32_bf16 v[18:21], v[142:145], v[186:189], v[18:21]
	v_mfma_f32_16x16x32_bf16 v[10:13], v[154:157], v[186:189], v[10:13]
	v_mfma_f32_16x16x32_bf16 v[62:65], v[150:153], v[166:169], v[62:65]
	v_mfma_f32_16x16x32_bf16 v[58:61], v[158:161], v[166:169], v[58:61]
	v_mfma_f32_16x16x32_bf16 v[50:53], v[150:153], v[174:177], v[50:53]
	v_mfma_f32_16x16x32_bf16 v[42:45], v[158:161], v[174:177], v[42:45]
	v_mfma_f32_16x16x32_bf16 v[34:37], v[150:153], v[182:185], v[34:37]
	v_mfma_f32_16x16x32_bf16 v[26:29], v[158:161], v[182:185], v[26:29]
	v_mfma_f32_16x16x32_bf16 v[18:21], v[150:153], v[190:193], v[18:21]
	v_mfma_f32_16x16x32_bf16 v[10:13], v[158:161], v[190:193], v[10:13]
	s_barrier
	s_add_u32 s18, s18, 0x80080
	s_addc_u32 s19, s19, 0
	s_add_i32 s20, s20, s23
	v_lshl_add_u64 v[142:143], s[18:19], 0, v[0:1]
	s_mov_b32 m0, s20
	s_nop 0
	global_load_lds_dwordx4 v[142:143], off
	v_lshl_add_u64 v[142:143], s[18:19], 0, v[130:131]
	s_add_i32 m0, s20, 0x2000
	s_nop 0
	global_load_lds_dwordx4 v[142:143], off
	s_waitcnt vmcnt(6)
	s_barrier
	v_mfma_f32_16x16x32_bf16 v[54:57], v[194:197], v[162:165], v[54:57]
	v_mfma_f32_16x16x32_bf16 v[46:49], v[202:205], v[162:165], v[46:49]
	v_mfma_f32_16x16x32_bf16 v[38:41], v[194:197], v[170:173], v[38:41]
	v_mfma_f32_16x16x32_bf16 v[30:33], v[202:205], v[170:173], v[30:33]
	v_mfma_f32_16x16x32_bf16 v[22:25], v[194:197], v[178:181], v[22:25]
	v_mfma_f32_16x16x32_bf16 v[14:17], v[202:205], v[178:181], v[14:17]
	v_mfma_f32_16x16x32_bf16 v[6:9], v[194:197], v[186:189], v[6:9]
	v_mfma_f32_16x16x32_bf16 v[2:5], v[202:205], v[186:189], v[2:5]
	v_mfma_f32_16x16x32_bf16 v[54:57], v[198:201], v[166:169], v[54:57]
	v_mfma_f32_16x16x32_bf16 v[46:49], v[206:209], v[166:169], v[46:49]
	v_mfma_f32_16x16x32_bf16 v[38:41], v[198:201], v[174:177], v[38:41]
	v_mfma_f32_16x16x32_bf16 v[30:33], v[206:209], v[174:177], v[30:33]
	v_mfma_f32_16x16x32_bf16 v[22:25], v[198:201], v[182:185], v[22:25]
	v_mfma_f32_16x16x32_bf16 v[14:17], v[206:209], v[182:185], v[14:17]
	v_mfma_f32_16x16x32_bf16 v[6:9], v[198:201], v[190:193], v[6:9]
	v_mfma_f32_16x16x32_bf16 v[2:5], v[206:209], v[190:193], v[2:5]
	s_add_i32 s38, s38, 2
	s_add_u32 s16, s16, 0x100
	s_addc_u32 s17, s17, 0
	s_add_u32 s36, s36, 0x100
	s_addc_u32 s37, s37, 0
	s_cmp_gt_u32 s38, 29
	s_barrier
	s_cbranch_scc0 .LBB0_342
	s_cmp_eq_u32 s3, 18
	s_cselect_b64 s[16:17], -1, 0
	v_lshl_add_u32 v142, s31, 8, v146
	s_and_b64 s[16:17], s[6:7], s[16:17]
	v_ashrrev_i32_e32 v143, 31, v142
	s_and_b64 s[16:17], s[16:17], s[0:1]
	s_and_saveexec_b64 s[18:19], s[16:17]
	s_cbranch_execz .LBB0_345
	v_lshlrev_b64 v[144:145], 6, v[142:143]
	v_lshl_add_u64 v[144:145], v[136:137], 0, v[144:145]
	global_store_dwordx4 v[144:145], v[126:129], off
	global_store_dwordx4 v[144:145], v[122:125], off offset:16

; #define PG8_STAGE(bufoff, gbase, voff) do { _Pragma("unroll") for (int _i = 0; _i < 2; ++_i) \
;         __builtin_amdgcn_global_load_lds((const unsigned*)((const char*)(gbase) + (voff)[_i]), (LAS unsigned*)(lds + (bufoff) + ldsw + _i * 8192), 16, 0, 0); } while (0)
; #define PG8_LDA(dst, b, h) do { _Pragma("unroll") for (int m = 0; m < 4; ++m) _Pragma("unroll") for (int k = 0; k < 2; ++k) dst[m][k] = *(const LAS bf16x8*)(lds + PG8_SA(b, h) + aoff + m * 2048 + k * 1024); } while (0)
; #define PG8_LDB(dst, b, h) do { _Pragma("unroll") for (int n = 0; n < 2; ++n) _Pragma("unroll") for (int k = 0; k < 2; ++k) dst[n][k] = *(const LAS bf16x8*)(lds + PG8_SB(b, h) + boff + n * 2048 + k * 1024); } while (0)
; #define PG8_MMA(ai, bj, At, Bt) do { __builtin_amdgcn_s_setprio(1); _Pragma("unroll") for (int m = 0; m < 4; ++m) _Pragma("unroll") for (int n = 0; n < 2; ++n) _Pragma("unroll") for (int k = 0; k < 2; ++k) \
;         acc[ai][bj][m][n] = __builtin_amdgcn_mfma_f32_16x16x32_bf16(Bt[n][k], At[m][k], acc[ai][bj][m][n], 0, 0, 0); __builtin_amdgcn_s_setprio(0); } while (0)
; #define PG8_WAIT_V(n) asm volatile("s_waitcnt vmcnt(" #n ")" ::: "memory")
; #define PG8_BAR __builtin_amdgcn_s_barrier()
; template <class Epi, class Sched>
; __device__ __forceinline__ void gemm_phase(LAS unsigned char* lds, const Gemm g, const Sched& S, const Epi& E) {
;     ...
;         for (int t = 0; t < nt; t += 2) {
;             const bool last = (t == nt - 2);
;             const char* a1 = cA + (size_t)(t + 1) * kstep;
;             const char* a2 = last ? nA : cA + (size_t)(t + 2) * kstep; const char* b2 = last ? nB : cB + (size_t)(t + 2) * kstep;
;             const char* a3 = a2 + kstep; const char* b3 = b2 + kstep;
;             if (last && has_next) S.a_ready(nxt);
;             PG8_LDB(B0, 0, 0); PG8_SCHED; PG8_LDA(At, 0, 0); PG8_STAGE(PG8_SA(1, 1), a1 + hstep, voffA);
;             PG8_WAIT_L(8); PG8_BAR; PG8_WAIT_L(0); PG8_MMA(0, 0, At, B0); PG8_BAR; PG8_SCHED;
;             PG8_LDB(B1, 0, 1); PG8_STAGE(PG8_SB(0, 0), b2, voffB);
;             PG8_BAR; PG8_WAIT_L(0); PG8_MMA(0, 1, At, B1); PG8_BAR;
;             PG8_LDA(At, 0, 1); PG8_STAGE(PG8_SA(0, 0), a2, voffA);
;             PG8_BAR; PG8_WAIT_L(0); PG8_MMA(1, 0, At, B0); PG8_BAR; PG8_SCHED;
;             PG8_STAGE(PG8_SB(0, 1), b2 + hstep, voffB);
;             PG8_WAIT_V(6); PG8_BAR; PG8_MMA(1, 1, At, B1); PG8_BAR;
.LBB0_1123:
	s_nop 0
	v_add_u32_e32 v0, s44, v151
	ds_read_b128 v[138:141], v0
	ds_read_b128 v[142:145], v0 offset:1024
	ds_read_b128 v[146:149], v0 offset:2048
	ds_read_b128 v[154:157], v0 offset:3072
	s_add_u32 s20, s18, 0x100
	s_addc_u32 s21, s19, 0
	s_cmp_eq_u32 s42, 28
	s_cselect_b32 s25, s3, s21
	s_cselect_b32 s24, s9, s20
	s_cselect_b32 s23, s1, s41
	s_cselect_b32 s22, s15, s17
	v_lshl_add_u64 v[190:191], s[18:19], 0, v[134:135]
	s_add_i32 m0, s31, 0xc000
	ds_read_b128 v[158:161], v153
	ds_read_b128 v[162:165], v153 offset:1024
	ds_read_b128 v[166:169], v153 offset:2048
	ds_read_b128 v[170:173], v153 offset:3072
	ds_read_b128 v[174:177], v153 offset:4096
	ds_read_b128 v[178:181], v153 offset:5120
	ds_read_b128 v[182:185], v153 offset:6144
	ds_read_b128 v[186:189], v153 offset:7168
	global_load_lds_dwordx4 v[190:191], off
	v_lshl_add_u64 v[190:191], s[18:19], 0, v[136:137]
	s_add_i32 m0, s31, 0xe000
	s_nop 0
	global_load_lds_dwordx4 v[190:191], off
	s_waitcnt lgkmcnt(8)
	s_barrier
	s_waitcnt lgkmcnt(0)
	s_waitcnt lgkmcnt(0)
	v_mfma_f32_16x16x32_bf16 v[126:129], v[138:141], v[158:161], v[126:129]
	v_mfma_f32_16x16x32_bf16 v[122:125], v[146:149], v[158:161], v[122:125]
	v_mfma_f32_16x16x32_bf16 v[110:113], v[138:141], v[166:169], v[110:113]
	v_mfma_f32_16x16x32_bf16 v[106:109], v[146:149], v[166:169], v[106:109]
	v_mfma_f32_16x16x32_bf16 v[94:97], v[138:141], v[174:177], v[94:97]
	v_mfma_f32_16x16x32_bf16 v[90:93], v[146:149], v[174:177], v[90:93]
	v_mfma_f32_16x16x32_bf16 v[78:81], v[138:141], v[182:185], v[78:81]
	v_mfma_f32_16x16x32_bf16 v[74:77], v[146:149], v[182:185], v[74:77]
	v_mfma_f32_16x16x32_bf16 v[126:129], v[142:145], v[162:165], v[126:129]
	v_mfma_f32_16x16x32_bf16 v[122:125], v[154:157], v[162:165], v[122:125]
	v_mfma_f32_16x16x32_bf16 v[110:113], v[142:145], v[170:173], v[110:113]
	v_mfma_f32_16x16x32_bf16 v[106:109], v[154:157], v[170:173], v[106:109]
	v_mfma_f32_16x16x32_bf16 v[94:97], v[142:145], v[178:181], v[94:97]
	v_mfma_f32_16x16x32_bf16 v[90:93], v[154:157], v[178:181], v[90:93]
	v_mfma_f32_16x16x32_bf16 v[78:81], v[142:145], v[186:189], v[78:81]
	v_mfma_f32_16x16x32_bf16 v[74:77], v[154:157], v[186:189], v[74:77]
	s_barrier
	s_add_i32 s43, 0, 0x14000
	s_add_i32 s18, s44, s30
	v_add_u32_e32 v0, s43, v151
	v_lshl_add_u64 v[206:207], s[22:23], 0, v[130:131]
	s_mov_b32 m0, s18
	ds_read_b128 v[190:193], v0
	ds_read_b128 v[194:197], v0 offset:1024
	ds_read_b128 v[198:201], v0 offset:2048
	ds_read_b128 v[202:205], v0 offset:3072
	global_load_lds_dwordx4 v[206:207], off
	v_lshl_add_u64 v[208:209], s[22:23], 0, v[132:133]
	s_add_i32 m0, s18, 0x2000
	s_nop 0
	global_load_lds_dwordx4 v[208:209], off
	s_barrier
	s_waitcnt lgkmcnt(0)
	s_waitcnt lgkmcnt(0)
	v_mfma_f32_16x16x32_bf16 v[118:121], v[190:193], v[158:161], v[118:121]
	v_mfma_f32_16x16x32_bf16 v[114:117], v[198:201], v[158:161], v[114:117]
	v_mfma_f32_16x16x32_bf16 v[102:105], v[190:193], v[166:169], v[102:105]
	v_mfma_f32_16x16x32_bf16 v[98:101], v[198:201], v[166:169], v[98:101]
	v_mfma_f32_16x16x32_bf16 v[86:89], v[190:193], v[174:177], v[86:89]
	v_mfma_f32_16x16x32_bf16 v[82:85], v[198:201], v[174:177], v[82:85]
	v_mfma_f32_16x16x32_bf16 v[70:73], v[190:193], v[182:185], v[70:73]
	v_mfma_f32_16x16x32_bf16 v[66:69], v[198:201], v[182:185], v[66:69]
	v_mfma_f32_16x16x32_bf16 v[118:121], v[194:197], v[162:165], v[118:121]
	v_mfma_f32_16x16x32_bf16 v[114:117], v[202:205], v[162:165], v[114:117]
	v_mfma_f32_16x16x32_bf16 v[102:105], v[194:197], v[170:173], v[102:105]
	v_mfma_f32_16x16x32_bf16 v[98:101], v[202:205], v[170:173], v[98:101]
	v_mfma_f32_16x16x32_bf16 v[86:89], v[194:197], v[178:181], v[86:89]
	v_mfma_f32_16x16x32_bf16 v[82:85], v[202:205], v[178:181], v[82:85]
	v_mfma_f32_16x16x32_bf16 v[70:73], v[194:197], v[186:189], v[70:73]
	v_mfma_f32_16x16x32_bf16 v[66:69], v[202:205], v[186:189], v[66:69]
	s_mov_b32 m0, s31
	v_lshl_add_u64 v[210:211], s[24:25], 0, v[130:131]
	s_barrier
	ds_read_b128 v[158:161], v153 offset:16384
	ds_read_b128 v[162:165], v153 offset:17408
	ds_read_b128 v[166:169], v153 offset:18432
	ds_read_b128 v[170:173], v153 offset:19456
	ds_read_b128 v[174:177], v153 offset:20480
	ds_read_b128 v[178:181], v153 offset:21504
	ds_read_b128 v[182:185], v153 offset:22528
	ds_read_b128 v[186:189], v153 offset:23552
	global_load_lds_dwordx4 v[210:211], off
	v_lshl_add_u64 v[220:221], s[24:25], 0, v[132:133]
	s_mov_b32 m0, s34
	s_nop 0
	global_load_lds_dwordx4 v[220:221], off
	s_barrier
	s_waitcnt lgkmcnt(0)
	s_waitcnt lgkmcnt(0)
	v_mfma_f32_16x16x32_bf16 v[62:65], v[138:141], v[158:161], v[62:65]
	v_mfma_f32_16x16x32_bf16 v[58:61], v[146:149], v[158:161], v[58:61]
	v_mfma_f32_16x16x32_bf16 v[46:49], v[138:141], v[166:169], v[46:49]
	v_mfma_f32_16x16x32_bf16 v[42:45], v[146:149], v[166:169], v[42:45]
	v_mfma_f32_16x16x32_bf16 v[30:33], v[138:141], v[174:177], v[30:33]
	v_mfma_f32_16x16x32_bf16 v[26:29], v[146:149], v[174:177], v[26:29]
	v_mfma_f32_16x16x32_bf16 v[14:17], v[138:141], v[182:185], v[14:17]
	v_mfma_f32_16x16x32_bf16 v[10:13], v[146:149], v[182:185], v[10:13]
	v_mfma_f32_16x16x32_bf16 v[62:65], v[142:145], v[162:165], v[62:65]
	v_mfma_f32_16x16x32_bf16 v[58:61], v[154:157], v[162:165], v[58:61]
	v_mfma_f32_16x16x32_bf16 v[46:49], v[142:145], v[170:173], v[46:49]
	v_mfma_f32_16x16x32_bf16 v[42:45], v[154:157], v[170:173], v[42:45]
	v_mfma_f32_16x16x32_bf16 v[30:33], v[142:145], v[178:181], v[30:33]
	v_mfma_f32_16x16x32_bf16 v[26:29], v[154:157], v[178:181], v[26:29]
	v_mfma_f32_16x16x32_bf16 v[14:17], v[142:145], v[186:189], v[14:17]
	v_mfma_f32_16x16x32_bf16 v[10:13], v[154:157], v[186:189], v[10:13]
	s_barrier
; #define PG8_STAGE(bufoff, gbase, voff) do { _Pragma("unroll") for (int _i = 0; _i < 2; ++_i) \
;         __builtin_amdgcn_global_load_lds((const unsigned*)((const char*)(gbase) + (voff)[_i]), (LAS unsigned*)(lds + (bufoff) + ldsw + _i * 8192), 16, 0, 0); } while (0)
; #define PG8_LDA(dst, b, h) do { _Pragma("unroll") for (int m = 0; m < 4; ++m) _Pragma("unroll") for (int k = 0; k < 2; ++k) dst[m][k] = *(const LAS bf16x8*)(lds + PG8_SA(b, h) + aoff + m * 2048 + k * 1024); } while (0)
; #define PG8_LDB(dst, b, h) do { _Pragma("unroll") for (int n = 0; n < 2; ++n) _Pragma("unroll") for (int k = 0; k < 2; ++k) dst[n][k] = *(const LAS bf16x8*)(lds + PG8_SB(b, h) + boff + n * 2048 + k * 1024); } while (0)
; #define PG8_MMA(ai, bj, At, Bt) do { __builtin_amdgcn_s_setprio(1); _Pragma("unroll") for (int m = 0; m < 4; ++m) _Pragma("unroll") for (int n = 0; n < 2; ++n) _Pragma("unroll") for (int k = 0; k < 2; ++k) \
;         acc[ai][bj][m][n] = __builtin_amdgcn_mfma_f32_16x16x32_bf16(Bt[n][k], At[m][k], acc[ai][bj][m][n], 0, 0, 0); __builtin_amdgcn_s_setprio(0); } while (0)
; #define PG8_WAIT_V(n) asm volatile("s_waitcnt vmcnt(" #n ")" ::: "memory")
; #define PG8_WAIT_L(n) asm volatile("s_waitcnt lgkmcnt(" #n ")" ::: "memory")
; #define PG8_BAR __builtin_amdgcn_s_barrier()
; #define PG8_SCHED __builtin_amdgcn_sched_barrier(0)
; template <class Epi, class Sched>
; __device__ __forceinline__ void gemm_phase(LAS unsigned char* lds, const Gemm g, const Sched& S, const Epi& E) {
;     ...
;             PG8_WAIT_V(6); PG8_BAR; PG8_MMA(1, 1, At, B1); PG8_BAR;
;             PG8_LDB(B0, 1, 0); PG8_SCHED; PG8_LDA(At, 1, 0); PG8_STAGE(PG8_SA(0, 1), a2 + hstep, voffA);
;             PG8_WAIT_L(8); PG8_BAR; PG8_WAIT_L(0); PG8_MMA(0, 0, At, B0); PG8_BAR; PG8_SCHED;
;             PG8_LDB(B1, 1, 1); PG8_STAGE(PG8_SB(1, 0), b3, voffB);
;             PG8_BAR; PG8_WAIT_L(0); PG8_MMA(0, 1, At, B1); PG8_BAR;
;             PG8_LDA(At, 1, 1); PG8_STAGE(PG8_SA(1, 0), a3, voffA);
;             PG8_BAR; PG8_WAIT_L(0); PG8_MMA(1, 0, At, B0); PG8_BAR; PG8_SCHED;
	s_add_u32 s18, s22, 0x80000
	s_addc_u32 s19, s23, 0
	s_add_i32 s43, s43, s30
	v_lshl_add_u64 v[138:139], s[18:19], 0, v[130:131]
	s_mov_b32 m0, s43
	s_nop 0
	global_load_lds_dwordx4 v[138:139], off
	v_lshl_add_u64 v[138:139], s[18:19], 0, v[132:133]
	s_add_i32 m0, s43, 0x2000
	s_nop 0
	global_load_lds_dwordx4 v[138:139], off
	s_waitcnt vmcnt(6)
	s_barrier
	v_mfma_f32_16x16x32_bf16 v[54:57], v[190:193], v[158:161], v[54:57]
	v_mfma_f32_16x16x32_bf16 v[50:53], v[198:201], v[158:161], v[50:53]
	v_mfma_f32_16x16x32_bf16 v[38:41], v[190:193], v[166:169], v[38:41]
	v_mfma_f32_16x16x32_bf16 v[34:37], v[198:201], v[166:169], v[34:37]
	v_mfma_f32_16x16x32_bf16 v[22:25], v[190:193], v[174:177], v[22:25]
	v_mfma_f32_16x16x32_bf16 v[18:21], v[198:201], v[174:177], v[18:21]
	v_mfma_f32_16x16x32_bf16 v[6:9], v[190:193], v[182:185], v[6:9]
	v_mfma_f32_16x16x32_bf16 v[2:5], v[198:201], v[182:185], v[2:5]
	v_mfma_f32_16x16x32_bf16 v[54:57], v[194:197], v[162:165], v[54:57]
	v_mfma_f32_16x16x32_bf16 v[50:53], v[202:205], v[162:165], v[50:53]
	v_mfma_f32_16x16x32_bf16 v[38:41], v[194:197], v[170:173], v[38:41]
	v_mfma_f32_16x16x32_bf16 v[34:37], v[202:205], v[170:173], v[34:37]
	v_mfma_f32_16x16x32_bf16 v[22:25], v[194:197], v[178:181], v[22:25]
	v_mfma_f32_16x16x32_bf16 v[18:21], v[202:205], v[178:181], v[18:21]
	v_mfma_f32_16x16x32_bf16 v[6:9], v[194:197], v[186:189], v[6:9]
	v_mfma_f32_16x16x32_bf16 v[2:5], v[202:205], v[186:189], v[2:5]
	s_add_i32 s43, 0, 0x18000
	v_add_u32_e32 v0, s43, v151
	s_barrier
	ds_read_b128 v[138:141], v0
	ds_read_b128 v[142:145], v0 offset:1024
	ds_read_b128 v[146:149], v0 offset:2048
	ds_read_b128 v[154:157], v0 offset:3072
	s_add_u32 s18, s24, 0x80000
	s_addc_u32 s19, s25, 0
	s_mov_b32 m0, s35
	v_lshl_add_u64 v[190:191], s[18:19], 0, v[130:131]
	ds_read_b128 v[158:161], v153 offset:32768
	ds_read_b128 v[162:165], v153 offset:33792
	ds_read_b128 v[166:169], v153 offset:34816
	ds_read_b128 v[170:173], v153 offset:35840
	ds_read_b128 v[174:177], v153 offset:36864
	ds_read_b128 v[178:181], v153 offset:37888
	ds_read_b128 v[182:185], v153 offset:38912
	ds_read_b128 v[186:189], v153 offset:39936
	global_load_lds_dwordx4 v[190:191], off
	v_lshl_add_u64 v[190:191], s[18:19], 0, v[132:133]
	s_mov_b32 m0, s36
	s_nop 0
	global_load_lds_dwordx4 v[190:191], off
	s_waitcnt lgkmcnt(8)
	s_barrier
	s_waitcnt lgkmcnt(0)
	s_waitcnt lgkmcnt(0)
	v_mfma_f32_16x16x32_bf16 v[126:129], v[138:141], v[158:161], v[126:129]
	v_mfma_f32_16x16x32_bf16 v[122:125], v[146:149], v[158:161], v[122:125]
	v_mfma_f32_16x16x32_bf16 v[110:113], v[138:141], v[166:169], v[110:113]
	v_mfma_f32_16x16x32_bf16 v[106:109], v[146:149], v[166:169], v[106:109]
	v_mfma_f32_16x16x32_bf16 v[94:97], v[138:141], v[174:177], v[94:97]
	v_mfma_f32_16x16x32_bf16 v[90:93], v[146:149], v[174:177], v[90:93]
	v_mfma_f32_16x16x32_bf16 v[78:81], v[138:141], v[182:185], v[78:81]
	v_mfma_f32_16x16x32_bf16 v[74:77], v[146:149], v[182:185], v[74:77]
	v_mfma_f32_16x16x32_bf16 v[126:129], v[142:145], v[162:165], v[126:129]
	v_mfma_f32_16x16x32_bf16 v[122:125], v[154:157], v[162:165], v[122:125]
	v_mfma_f32_16x16x32_bf16 v[110:113], v[142:145], v[170:173], v[110:113]
	v_mfma_f32_16x16x32_bf16 v[106:109], v[154:157], v[170:173], v[106:109]
	v_mfma_f32_16x16x32_bf16 v[94:97], v[142:145], v[178:181], v[94:97]
	v_mfma_f32_16x16x32_bf16 v[90:93], v[154:157], v[178:181], v[90:93]
	v_mfma_f32_16x16x32_bf16 v[78:81], v[142:145], v[186:189], v[78:81]
	v_mfma_f32_16x16x32_bf16 v[74:77], v[154:157], v[186:189], v[74:77]
	s_barrier
	s_add_i32 s24, 0, 0x1c000
	s_add_i32 s18, s43, s30
	v_add_u32_e32 v0, s24, v151
	v_lshl_add_u64 v[206:207], v[206:207], 0, s[46:47]
	s_mov_b32 m0, s18
	ds_read_b128 v[190:193], v0
	ds_read_b128 v[194:197], v0 offset:1024
	ds_read_b128 v[198:201], v0 offset:2048
	ds_read_b128 v[202:205], v0 offset:3072
	global_load_lds_dwordx4 v[206:207], off
	v_lshl_add_u64 v[206:207], v[208:209], 0, s[46:47]
	s_add_i32 m0, s18, 0x2000
	s_nop 0
	global_load_lds_dwordx4 v[206:207], off
	s_barrier
	s_waitcnt lgkmcnt(0)
	s_waitcnt lgkmcnt(0)
	v_mfma_f32_16x16x32_bf16 v[118:121], v[190:193], v[158:161], v[118:121]
	v_mfma_f32_16x16x32_bf16 v[114:117], v[198:201], v[158:161], v[114:117]
	v_mfma_f32_16x16x32_bf16 v[102:105], v[190:193], v[166:169], v[102:105]
	v_mfma_f32_16x16x32_bf16 v[98:101], v[198:201], v[166:169], v[98:101]
	v_mfma_f32_16x16x32_bf16 v[86:89], v[190:193], v[174:177], v[86:89]
	v_mfma_f32_16x16x32_bf16 v[82:85], v[198:201], v[174:177], v[82:85]
	v_mfma_f32_16x16x32_bf16 v[70:73], v[190:193], v[182:185], v[70:73]
	v_mfma_f32_16x16x32_bf16 v[66:69], v[198:201], v[182:185], v[66:69]
	v_mfma_f32_16x16x32_bf16 v[118:121], v[194:197], v[162:165], v[118:121]
	v_mfma_f32_16x16x32_bf16 v[114:117], v[202:205], v[162:165], v[114:117]
	v_mfma_f32_16x16x32_bf16 v[102:105], v[194:197], v[170:173], v[102:105]
	v_mfma_f32_16x16x32_bf16 v[98:101], v[202:205], v[170:173], v[98:101]
	v_mfma_f32_16x16x32_bf16 v[86:89], v[194:197], v[178:181], v[86:89]
	v_mfma_f32_16x16x32_bf16 v[82:85], v[202:205], v[178:181], v[82:85]
	v_mfma_f32_16x16x32_bf16 v[70:73], v[194:197], v[186:189], v[70:73]
	v_mfma_f32_16x16x32_bf16 v[66:69], v[202:205], v[186:189], v[66:69]
	s_mov_b32 m0, s38
	v_lshl_add_u64 v[206:207], v[210:211], 0, s[46:47]
	s_barrier
	ds_read_b128 v[158:161], v153 offset:49152
	ds_read_b128 v[162:165], v153 offset:50176
	ds_read_b128 v[166:169], v153 offset:51200
	ds_read_b128 v[170:173], v153 offset:52224
	ds_read_b128 v[174:177], v153 offset:53248
	ds_read_b128 v[178:181], v153 offset:54272
	ds_read_b128 v[182:185], v153 offset:55296
	ds_read_b128 v[186:189], v153 offset:56320
	global_load_lds_dwordx4 v[206:207], off
	v_lshl_add_u64 v[206:207], v[220:221], 0, s[46:47]
	s_mov_b32 m0, s39
	s_nop 0
	global_load_lds_dwordx4 v[206:207], off
	s_barrier
; #define PG8_STAGE(bufoff, gbase, voff) do { _Pragma("unroll") for (int _i = 0; _i < 2; ++_i) \
;         __builtin_amdgcn_global_load_lds((const unsigned*)((const char*)(gbase) + (voff)[_i]), (LAS unsigned*)(lds + (bufoff) + ldsw + _i * 8192), 16, 0, 0); } while (0)
; #define PG8_MMA(ai, bj, At, Bt) do { __builtin_amdgcn_s_setprio(1); _Pragma("unroll") for (int m = 0; m < 4; ++m) _Pragma("unroll") for (int n = 0; n < 2; ++n) _Pragma("unroll") for (int k = 0; k < 2; ++k) \
;         acc[ai][bj][m][n] = __builtin_amdgcn_mfma_f32_16x16x32_bf16(Bt[n][k], At[m][k], acc[ai][bj][m][n], 0, 0, 0); __builtin_amdgcn_s_setprio(0); } while (0)
; #define PG8_WAIT_V(n) asm volatile("s_waitcnt vmcnt(" #n ")" ::: "memory")
; #define PG8_WAIT_L(n) asm volatile("s_waitcnt lgkmcnt(" #n ")" ::: "memory")
; #define PG8_BAR __builtin_amdgcn_s_barrier()
; template <class Epi, class Sched>
; __device__ __forceinline__ void gemm_phase(LAS unsigned char* lds, const Gemm g, const Sched& S, const Epi& E) {
;     ...
;             PG8_BAR; PG8_WAIT_L(0); PG8_MMA(1, 0, At, B0); PG8_BAR; PG8_SCHED;
;             PG8_STAGE(PG8_SB(1, 1), b3 + hstep, voffB);
;             PG8_WAIT_V(6); PG8_BAR; PG8_MMA(1, 1, At, B1); PG8_BAR;
;         }
;         E(acc, cur, wr, wc, fr, fq); S.done(cur);
;     __device__ __forceinline__ void operator()(const f32x4 (&acc)[2][2][4][2], const pg8::Unit& u, int wr, int wc, int fr, int fq) const {
;         const int row0 = u.pm * 256 + wr * 64 + fr; const int col0 = u.pn * 256 + wc * 32 + 4 * fq;
; #pragma unroll
;         for (int ai = 0; ai < 2; ++ai)
; #pragma unroll
;             for (int m = 0; m < 4; ++m) { const int row = row0 + ai * 128 + m * 16;
;                 const float* ip; float* op; int b;
;                 if (row < ML_ROWS) { b = row >> 11; ip = xi + (size_t)row * D; op = xo + (size_t)row * D; }
;                 else { b = 8; ip = ci + (size_t)(row - ML_ROWS) * D; op = co + (size_t)(row - ML_ROWS) * D; }
;                 const float* gp = mod + (size_t)b * 12288 + slot * 2048;
; #pragma unroll
;                 for (int bj = 0; bj < 2; ++bj)
; #pragma unroll
;                     for (int n = 0; n < 2; ++n) { const int c = col0 + bj * 128 + n * 16;
;                         const f32x4 r = *(const f32x4*)(ip + c), g = *(const f32x4*)(gp + c);
;                         *(f32x4*)(op + c) = r + g * acc[ai][bj][m][n]; } }
	s_waitcnt lgkmcnt(0)
	s_waitcnt lgkmcnt(0)
	v_mfma_f32_16x16x32_bf16 v[62:65], v[138:141], v[158:161], v[62:65]
	v_mfma_f32_16x16x32_bf16 v[58:61], v[146:149], v[158:161], v[58:61]
	v_mfma_f32_16x16x32_bf16 v[46:49], v[138:141], v[166:169], v[46:49]
	v_mfma_f32_16x16x32_bf16 v[42:45], v[146:149], v[166:169], v[42:45]
	v_mfma_f32_16x16x32_bf16 v[30:33], v[138:141], v[174:177], v[30:33]
	v_mfma_f32_16x16x32_bf16 v[26:29], v[146:149], v[174:177], v[26:29]
	v_mfma_f32_16x16x32_bf16 v[14:17], v[138:141], v[182:185], v[14:17]
	v_mfma_f32_16x16x32_bf16 v[10:13], v[146:149], v[182:185], v[10:13]
	v_mfma_f32_16x16x32_bf16 v[62:65], v[142:145], v[162:165], v[62:65]
	v_mfma_f32_16x16x32_bf16 v[58:61], v[154:157], v[162:165], v[58:61]
	v_mfma_f32_16x16x32_bf16 v[46:49], v[142:145], v[170:173], v[46:49]
	v_mfma_f32_16x16x32_bf16 v[42:45], v[154:157], v[170:173], v[42:45]
	v_mfma_f32_16x16x32_bf16 v[30:33], v[142:145], v[178:181], v[30:33]
	v_mfma_f32_16x16x32_bf16 v[26:29], v[154:157], v[178:181], v[26:29]
	v_mfma_f32_16x16x32_bf16 v[14:17], v[142:145], v[186:189], v[14:17]
	v_mfma_f32_16x16x32_bf16 v[10:13], v[154:157], v[186:189], v[10:13]
	s_barrier
	s_add_u32 s18, s22, 0x80080
	s_addc_u32 s19, s23, 0
	s_add_i32 s22, s24, s30
	v_lshl_add_u64 v[138:139], s[18:19], 0, v[130:131]
	s_mov_b32 m0, s22
	s_nop 0
	global_load_lds_dwordx4 v[138:139], off
	v_lshl_add_u64 v[138:139], s[18:19], 0, v[132:133]
	s_add_i32 m0, s22, 0x2000
	s_nop 0
	global_load_lds_dwordx4 v[138:139], off
	s_waitcnt vmcnt(6)
	s_barrier
	v_mfma_f32_16x16x32_bf16 v[54:57], v[190:193], v[158:161], v[54:57]
	v_mfma_f32_16x16x32_bf16 v[50:53], v[198:201], v[158:161], v[50:53]
	v_mfma_f32_16x16x32_bf16 v[38:41], v[190:193], v[166:169], v[38:41]
	v_mfma_f32_16x16x32_bf16 v[34:37], v[198:201], v[166:169], v[34:37]
	v_mfma_f32_16x16x32_bf16 v[22:25], v[190:193], v[174:177], v[22:25]
	v_mfma_f32_16x16x32_bf16 v[18:21], v[198:201], v[174:177], v[18:21]
	v_mfma_f32_16x16x32_bf16 v[6:9], v[190:193], v[182:185], v[6:9]
	v_mfma_f32_16x16x32_bf16 v[2:5], v[198:201], v[182:185], v[2:5]
	v_mfma_f32_16x16x32_bf16 v[54:57], v[194:197], v[162:165], v[54:57]
	v_mfma_f32_16x16x32_bf16 v[50:53], v[202:205], v[162:165], v[50:53]
	v_mfma_f32_16x16x32_bf16 v[38:41], v[194:197], v[170:173], v[38:41]
	v_mfma_f32_16x16x32_bf16 v[34:37], v[202:205], v[170:173], v[34:37]
	v_mfma_f32_16x16x32_bf16 v[22:25], v[194:197], v[178:181], v[22:25]
	v_mfma_f32_16x16x32_bf16 v[18:21], v[202:205], v[178:181], v[18:21]
	v_mfma_f32_16x16x32_bf16 v[6:9], v[194:197], v[186:189], v[6:9]
	v_mfma_f32_16x16x32_bf16 v[2:5], v[202:205], v[186:189], v[2:5]
	s_add_i32 s42, s42, 2
	s_add_u32 s17, s17, 0x100
	s_addc_u32 s41, s41, 0
	s_cmp_gt_u32 s42, 29
	s_mov_b64 s[18:19], s[20:21]
	s_barrier
	s_cbranch_scc0 .LBB0_1123
	s_lshl_b32 s1, s16, 8
	s_add_i32 s1, s1, s37
	v_readlane_b32 s44, v251, 0
	v_readlane_b32 s45, v251, 1
	v_readlane_b32 s46, v251, 2
	v_readlane_b32 s47, v251, 3
	v_readlane_b32 s48, v251, 4
	v_readlane_b32 s49, v251, 5
	v_readlane_b32 s50, v251, 6
	v_readlane_b32 s51, v251, 7
	v_readlane_b32 s22, v254, 4
	v_readlane_b32 s23, v254, 5
	v_readlane_b32 s20, v254, 6
	v_readlane_b32 s21, v254, 7
	v_readlane_b32 s18, v254, 2
	v_readlane_b32 s19, v254, 3
	s_add_i32 s3, s1, 0xffffc000
	s_ashr_i32 s15, s1, 11
	s_cmpk_lt_i32 s1, 0x4000
	s_cselect_b32 s22, s22, s20
	s_cselect_b32 s23, s23, s21
	s_cselect_b32 s20, s46, s60
	s_cselect_b32 s21, s47, s61
	s_cselect_b32 s3, s1, s3
	s_cselect_b32 s15, s15, 8
	s_mul_i32 s15, s15, 0xc000
	s_add_u32 s18, s18, s15
	s_addc_u32 s19, s19, 0
	s_add_u32 s18, s18, 0x4000
	s_addc_u32 s19, s19, 0
	v_add_u32_e32 v138, s3, v150
	v_lshl_or_b32 v139, s14, 8, v152
	v_lshlrev_b32_e32 v139, 2, v139
	v_lshl_or_b32 v138, v138, 13, v139
	v_add_u32_e32 v140, 0x20000, v138
	v_add_u32_e32 v141, 0x40000, v138
	v_add_u32_e32 v0, 0x60000, v138
	v_add_u32_e32 v210, 0x100000, v138
	v_add_u32_e32 v211, 0x120000, v138
	v_add_u32_e32 v220, 0x140000, v138
	global_load_dwordx4 v[154:157], v139, s[18:19]
	global_load_dwordx4 v[158:161], v139, s[18:19] offset:64
	global_load_dwordx4 v[162:165], v139, s[18:19] offset:512
	global_load_dwordx4 v[166:169], v139, s[18:19] offset:576
	v_add_u32_e32 v139, 0x160000, v138
	global_load_dwordx4 v[170:173], v138, s[22:23]
	global_load_dwordx4 v[174:177], v138, s[22:23] offset:64
	global_load_dwordx4 v[178:181], v138, s[22:23] offset:512
	global_load_dwordx4 v[182:185], v138, s[22:23] offset:576
	global_load_dwordx4 v[186:189], v140, s[22:23]
	global_load_dwordx4 v[190:193], v140, s[22:23] offset:64
	global_load_dwordx4 v[194:197], v140, s[22:23] offset:512
	global_load_dwordx4 v[198:201], v140, s[22:23] offset:576
	global_load_dwordx4 v[202:205], v141, s[22:23]
	global_load_dwordx4 v[206:209], v141, s[22:23] offset:64
	global_load_dwordx4 v[142:145], v141, s[22:23] offset:512
	global_load_dwordx4 v[146:149], v141, s[22:23] offset:576
	s_waitcnt vmcnt(8)
	v_pk_fma_f32 v[126:127], v[126:127], v[154:155], v[170:171]
	v_pk_fma_f32 v[128:129], v[128:129], v[156:157], v[172:173]
	v_pk_fma_f32 v[122:123], v[122:123], v[158:159], v[174:175]
	v_pk_fma_f32 v[124:125], v[124:125], v[160:161], v[176:177]
	v_pk_fma_f32 v[118:119], v[118:119], v[162:163], v[178:179]
	v_pk_fma_f32 v[120:121], v[120:121], v[164:165], v[180:181]
	v_pk_fma_f32 v[114:115], v[114:115], v[166:167], v[182:183]
	v_pk_fma_f32 v[116:117], v[116:117], v[168:169], v[184:185]
	global_store_dwordx4 v138, v[126:129], s[20:21]
	global_store_dwordx4 v138, v[122:125], s[20:21] offset:64
	global_store_dwordx4 v138, v[118:121], s[20:21] offset:512
	global_store_dwordx4 v138, v[114:117], s[20:21] offset:576
	global_load_dwordx4 v[170:173], v0, s[22:23]
	global_load_dwordx4 v[174:177], v0, s[22:23] offset:64
	global_load_dwordx4 v[178:181], v0, s[22:23] offset:512
	global_load_dwordx4 v[182:185], v0, s[22:23] offset:576
	s_waitcnt vmcnt(12)
;     __device__ __forceinline__ void operator()(const f32x4 (&acc)[2][2][4][2], const pg8::Unit& u, int wr, int wc, int fr, int fq) const {
;         const int row0 = u.pm * 256 + wr * 64 + fr; const int col0 = u.pn * 256 + wc * 32 + 4 * fq;
; #pragma unroll
;         for (int ai = 0; ai < 2; ++ai)
; #pragma unroll
;             for (int m = 0; m < 4; ++m) { const int row = row0 + ai * 128 + m * 16;
;                 const float* ip; float* op; int b;
;                 if (row < ML_ROWS) { b = row >> 11; ip = xi + (size_t)row * D; op = xo + (size_t)row * D; }
;                 else { b = 8; ip = ci + (size_t)(row - ML_ROWS) * D; op = co + (size_t)(row - ML_ROWS) * D; }
;                 const float* gp = mod + (size_t)b * 12288 + slot * 2048;
; #pragma unroll
;                 for (int bj = 0; bj < 2; ++bj)
; #pragma unroll
;                     for (int n = 0; n < 2; ++n) { const int c = col0 + bj * 128 + n * 16;
;                         const f32x4 r = *(const f32x4*)(ip + c), g = *(const f32x4*)(gp + c);
;                         *(f32x4*)(op + c) = r + g * acc[ai][bj][m][n]; } }
	v_pk_fma_f32 v[110:111], v[110:111], v[154:155], v[186:187]
	v_pk_fma_f32 v[112:113], v[112:113], v[156:157], v[188:189]
	v_pk_fma_f32 v[106:107], v[106:107], v[158:159], v[190:191]
	v_pk_fma_f32 v[108:109], v[108:109], v[160:161], v[192:193]
	v_pk_fma_f32 v[102:103], v[102:103], v[162:163], v[194:195]
	v_pk_fma_f32 v[104:105], v[104:105], v[164:165], v[196:197]
	v_pk_fma_f32 v[98:99], v[98:99], v[166:167], v[198:199]
	v_pk_fma_f32 v[100:101], v[100:101], v[168:169], v[200:201]
	global_store_dwordx4 v140, v[110:113], s[20:21]
	global_store_dwordx4 v140, v[106:109], s[20:21] offset:64
	global_store_dwordx4 v140, v[102:105], s[20:21] offset:512
	global_store_dwordx4 v140, v[98:101], s[20:21] offset:576
	global_load_dwordx4 v[186:189], v210, s[22:23]
	global_load_dwordx4 v[190:193], v210, s[22:23] offset:64
	global_load_dwordx4 v[194:197], v210, s[22:23] offset:512
	global_load_dwordx4 v[198:201], v210, s[22:23] offset:576
	s_waitcnt vmcnt(16)
	v_pk_fma_f32 v[94:95], v[94:95], v[154:155], v[202:203]
	v_pk_fma_f32 v[96:97], v[96:97], v[156:157], v[204:205]
	v_pk_fma_f32 v[90:91], v[90:91], v[158:159], v[206:207]
	v_pk_fma_f32 v[92:93], v[92:93], v[160:161], v[208:209]
	v_pk_fma_f32 v[86:87], v[86:87], v[162:163], v[142:143]
	v_pk_fma_f32 v[88:89], v[88:89], v[164:165], v[144:145]
	v_pk_fma_f32 v[82:83], v[82:83], v[166:167], v[146:147]
	v_pk_fma_f32 v[84:85], v[84:85], v[168:169], v[148:149]
	global_store_dwordx4 v141, v[94:97], s[20:21]
	global_store_dwordx4 v141, v[90:93], s[20:21] offset:64
	global_store_dwordx4 v141, v[86:89], s[20:21] offset:512
	global_store_dwordx4 v141, v[82:85], s[20:21] offset:576
	global_load_dwordx4 v[202:205], v211, s[22:23]
	global_load_dwordx4 v[206:209], v211, s[22:23] offset:64
	global_load_dwordx4 v[142:145], v211, s[22:23] offset:512
	global_load_dwordx4 v[146:149], v211, s[22:23] offset:576
	s_waitcnt vmcnt(16)
	v_pk_fma_f32 v[78:79], v[78:79], v[154:155], v[170:171]
	v_pk_fma_f32 v[80:81], v[80:81], v[156:157], v[172:173]
	v_pk_fma_f32 v[74:75], v[74:75], v[158:159], v[174:175]
	v_pk_fma_f32 v[76:77], v[76:77], v[160:161], v[176:177]
	v_pk_fma_f32 v[70:71], v[70:71], v[162:163], v[178:179]
	v_pk_fma_f32 v[72:73], v[72:73], v[164:165], v[180:181]
	v_pk_fma_f32 v[66:67], v[66:67], v[166:167], v[182:183]
	v_pk_fma_f32 v[68:69], v[68:69], v[168:169], v[184:185]
	global_store_dwordx4 v0, v[78:81], s[20:21]
	global_store_dwordx4 v0, v[74:77], s[20:21] offset:64
	global_store_dwordx4 v0, v[70:73], s[20:21] offset:512
	global_store_dwordx4 v0, v[66:69], s[20:21] offset:576
	global_load_dwordx4 v[170:173], v220, s[22:23]
	global_load_dwordx4 v[174:177], v220, s[22:23] offset:64
	global_load_dwordx4 v[178:181], v220, s[22:23] offset:512
	global_load_dwordx4 v[182:185], v220, s[22:23] offset:576
	s_waitcnt vmcnt(16)
	v_pk_fma_f32 v[62:63], v[62:63], v[154:155], v[186:187]
	v_pk_fma_f32 v[64:65], v[64:65], v[156:157], v[188:189]
	v_pk_fma_f32 v[58:59], v[58:59], v[158:159], v[190:191]
	v_pk_fma_f32 v[60:61], v[60:61], v[160:161], v[192:193]
	v_pk_fma_f32 v[54:55], v[54:55], v[162:163], v[194:195]
	v_pk_fma_f32 v[56:57], v[56:57], v[164:165], v[196:197]
	v_pk_fma_f32 v[50:51], v[50:51], v[166:167], v[198:199]
	v_pk_fma_f32 v[52:53], v[52:53], v[168:169], v[200:201]
	global_store_dwordx4 v210, v[62:65], s[20:21]
	global_store_dwordx4 v210, v[58:61], s[20:21] offset:64
	global_store_dwordx4 v210, v[54:57], s[20:21] offset:512
	global_store_dwordx4 v210, v[50:53], s[20:21] offset:576
	global_load_dwordx4 v[186:189], v139, s[22:23]
	global_load_dwordx4 v[190:193], v139, s[22:23] offset:64
	global_load_dwordx4 v[194:197], v139, s[22:23] offset:512
	global_load_dwordx4 v[198:201], v139, s[22:23] offset:576
	s_waitcnt vmcnt(16)
	v_pk_fma_f32 v[46:47], v[46:47], v[154:155], v[202:203]
	v_pk_fma_f32 v[48:49], v[48:49], v[156:157], v[204:205]
	v_pk_fma_f32 v[42:43], v[42:43], v[158:159], v[206:207]
	v_pk_fma_f32 v[44:45], v[44:45], v[160:161], v[208:209]
	v_pk_fma_f32 v[38:39], v[38:39], v[162:163], v[142:143]
	v_pk_fma_f32 v[40:41], v[40:41], v[164:165], v[144:145]
	v_pk_fma_f32 v[34:35], v[34:35], v[166:167], v[146:147]
	v_pk_fma_f32 v[36:37], v[36:37], v[168:169], v[148:149]
	global_store_dwordx4 v211, v[46:49], s[20:21]
	global_store_dwordx4 v211, v[42:45], s[20:21] offset:64
	global_store_dwordx4 v211, v[38:41], s[20:21] offset:512
	global_store_dwordx4 v211, v[34:37], s[20:21] offset:576
	s_waitcnt vmcnt(12)
	v_pk_fma_f32 v[30:31], v[30:31], v[154:155], v[170:171]
	v_pk_fma_f32 v[32:33], v[32:33], v[156:157], v[172:173]
	v_pk_fma_f32 v[26:27], v[26:27], v[158:159], v[174:175]
	v_pk_fma_f32 v[28:29], v[28:29], v[160:161], v[176:177]
	v_pk_fma_f32 v[22:23], v[22:23], v[162:163], v[178:179]
	v_pk_fma_f32 v[24:25], v[24:25], v[164:165], v[180:181]
	v_pk_fma_f32 v[18:19], v[18:19], v[166:167], v[182:183]
	v_pk_fma_f32 v[20:21], v[20:21], v[168:169], v[184:185]
	global_store_dwordx4 v220, v[30:33], s[20:21]
	global_store_dwordx4 v220, v[26:29], s[20:21] offset:64
	global_store_dwordx4 v220, v[22:25], s[20:21] offset:512
	global_store_dwordx4 v220, v[18:21], s[20:21] offset:576
	s_waitcnt vmcnt(8)
	v_pk_fma_f32 v[14:15], v[14:15], v[154:155], v[186:187]
	v_pk_fma_f32 v[16:17], v[16:17], v[156:157], v[188:189]
	v_pk_fma_f32 v[10:11], v[10:11], v[158:159], v[190:191]
	v_pk_fma_f32 v[12:13], v[12:13], v[160:161], v[192:193]
	v_pk_fma_f32 v[6:7], v[6:7], v[162:163], v[194:195]
	v_pk_fma_f32 v[8:9], v[8:9], v[164:165], v[196:197]
	v_pk_fma_f32 v[2:3], v[2:3], v[166:167], v[198:199]
	v_pk_fma_f32 v[4:5], v[4:5], v[168:169], v[200:201]
	global_store_dwordx4 v139, v[14:17], s[20:21]
	global_store_dwordx4 v139, v[10:13], s[20:21] offset:64
	global_store_dwordx4 v139, v[6:9], s[20:21] offset:512
	global_store_dwordx4 v139, v[2:5], s[20:21] offset:576
	v_mov_b32_e32 v170, v219
	s_mov_b32 s14, s0
	s_mov_b32 s16, s8
	s_mov_b64 s[20:21], s[12:13]
	s_mov_b64 s[18:19], s[10:11]
	s_and_b64 vcc, exec, s[4:5]
	s_cbranch_vccnz .LBB0_1156
	s_branch .LBB0_1120

; #define PG8_STAGE(bufoff, gbase, voff) do { _Pragma("unroll") for (int _i = 0; _i < 2; ++_i) \
;         __builtin_amdgcn_global_load_lds((const unsigned*)((const char*)(gbase) + (voff)[_i]), (LAS unsigned*)(lds + (bufoff) + ldsw + _i * 8192), 16, 0, 0); } while (0)
; #define PG8_LDA(dst, b, h) do { _Pragma("unroll") for (int m = 0; m < 4; ++m) _Pragma("unroll") for (int k = 0; k < 2; ++k) dst[m][k] = *(const LAS bf16x8*)(lds + PG8_SA(b, h) + aoff + m * 2048 + k * 1024); } while (0)
; #define PG8_LDB(dst, b, h) do { _Pragma("unroll") for (int n = 0; n < 2; ++n) _Pragma("unroll") for (int k = 0; k < 2; ++k) dst[n][k] = *(const LAS bf16x8*)(lds + PG8_SB(b, h) + boff + n * 2048 + k * 1024); } while (0)
; #define PG8_MMA(ai, bj, At, Bt) do { __builtin_amdgcn_s_setprio(1); _Pragma("unroll") for (int m = 0; m < 4; ++m) _Pragma("unroll") for (int n = 0; n < 2; ++n) _Pragma("unroll") for (int k = 0; k < 2; ++k) \
;         acc[ai][bj][m][n] = __builtin_amdgcn_mfma_f32_16x16x32_bf16(Bt[n][k], At[m][k], acc[ai][bj][m][n], 0, 0, 0); __builtin_amdgcn_s_setprio(0); } while (0)
; #define PG8_WAIT_V(n) asm volatile("s_waitcnt vmcnt(" #n ")" ::: "memory")
; #define PG8_BAR __builtin_amdgcn_s_barrier()
; template <class Epi, class Sched>
; __device__ __forceinline__ void gemm_phase(LAS unsigned char* lds, const Gemm g, const Sched& S, const Epi& E) {
;     ...
;         for (int t = 0; t < nt; t += 2) {
;             const bool last = (t == nt - 2);
;             const char* a1 = cA + (size_t)(t + 1) * kstep;
;             const char* a2 = last ? nA : cA + (size_t)(t + 2) * kstep; const char* b2 = last ? nB : cB + (size_t)(t + 2) * kstep;
;             const char* a3 = a2 + kstep; const char* b3 = b2 + kstep;
;             if (last && has_next) S.a_ready(nxt);
;             PG8_LDB(B0, 0, 0); PG8_SCHED; PG8_LDA(At, 0, 0); PG8_STAGE(PG8_SA(1, 1), a1 + hstep, voffA);
;             PG8_WAIT_L(8); PG8_BAR; PG8_WAIT_L(0); PG8_MMA(0, 0, At, B0); PG8_BAR; PG8_SCHED;
;             PG8_LDB(B1, 0, 1); PG8_STAGE(PG8_SB(0, 0), b2, voffB);
;             PG8_BAR; PG8_WAIT_L(0); PG8_MMA(0, 1, At, B1); PG8_BAR;
;             PG8_LDA(At, 0, 1); PG8_STAGE(PG8_SA(0, 0), a2, voffA);
;             PG8_BAR; PG8_WAIT_L(0); PG8_MMA(1, 0, At, B0); PG8_BAR; PG8_SCHED;
;             PG8_STAGE(PG8_SB(0, 1), b2 + hstep, voffB);
;             PG8_WAIT_V(6); PG8_BAR; PG8_MMA(1, 1, At, B1); PG8_BAR;
.LBB0_1279:
	s_nop 0
	v_add_u32_e32 v140, s47, v143
	ds_read_b128 v[146:149], v140
	ds_read_b128 v[150:153], v140 offset:1024
	ds_read_b128 v[154:157], v140 offset:2048
	ds_read_b128 v[158:161], v140 offset:3072
	s_add_u32 s22, s20, 0xfff80080
	s_addc_u32 s23, s21, -1
	s_cmp_eq_u32 s43, 28
	s_cselect_b32 s25, s3, s23
	s_cselect_b32 s24, s11, s22
	s_cselect_b32 s23, s9, s42
	s_cselect_b32 s22, s40, s41
	v_lshl_add_u64 v[140:141], s[20:21], 0, v[136:137]
	s_add_i32 m0, s17, 0xc000
	ds_read_b128 v[162:165], v145
	ds_read_b128 v[166:169], v145 offset:1024
	ds_read_b128 v[170:173], v145 offset:2048
	ds_read_b128 v[174:177], v145 offset:3072
	ds_read_b128 v[178:181], v145 offset:4096
	ds_read_b128 v[182:185], v145 offset:5120
	ds_read_b128 v[186:189], v145 offset:6144
	ds_read_b128 v[190:193], v145 offset:7168
	global_load_lds_dwordx4 v[140:141], off
	v_lshl_add_u64 v[140:141], s[20:21], 0, v[138:139]
	s_add_i32 m0, s17, 0xe000
	s_nop 0
	global_load_lds_dwordx4 v[140:141], off
	s_waitcnt lgkmcnt(8)
	s_barrier
	s_waitcnt lgkmcnt(0)
	s_waitcnt lgkmcnt(0)
	v_mfma_f32_16x16x32_bf16 v[126:129], v[146:149], v[162:165], v[126:129]
	v_mfma_f32_16x16x32_bf16 v[122:125], v[154:157], v[162:165], v[122:125]
	v_mfma_f32_16x16x32_bf16 v[110:113], v[146:149], v[170:173], v[110:113]
	v_mfma_f32_16x16x32_bf16 v[106:109], v[154:157], v[170:173], v[106:109]
	v_mfma_f32_16x16x32_bf16 v[94:97], v[146:149], v[178:181], v[94:97]
	v_mfma_f32_16x16x32_bf16 v[90:93], v[154:157], v[178:181], v[90:93]
	v_mfma_f32_16x16x32_bf16 v[78:81], v[146:149], v[186:189], v[78:81]
	v_mfma_f32_16x16x32_bf16 v[74:77], v[154:157], v[186:189], v[74:77]
	v_mfma_f32_16x16x32_bf16 v[126:129], v[150:153], v[166:169], v[126:129]
	v_mfma_f32_16x16x32_bf16 v[122:125], v[158:161], v[166:169], v[122:125]
	v_mfma_f32_16x16x32_bf16 v[110:113], v[150:153], v[174:177], v[110:113]
	v_mfma_f32_16x16x32_bf16 v[106:109], v[158:161], v[174:177], v[106:109]
	v_mfma_f32_16x16x32_bf16 v[94:97], v[150:153], v[182:185], v[94:97]
	v_mfma_f32_16x16x32_bf16 v[90:93], v[158:161], v[182:185], v[90:93]
	v_mfma_f32_16x16x32_bf16 v[78:81], v[150:153], v[190:193], v[78:81]
	v_mfma_f32_16x16x32_bf16 v[74:77], v[158:161], v[190:193], v[74:77]
	s_barrier
	s_add_i32 s46, 0, 0x14000
	v_add_u32_e32 v140, s46, v143
	s_add_i32 s44, s47, s30
	ds_read_b128 v[194:197], v140
	ds_read_b128 v[198:201], v140 offset:1024
	ds_read_b128 v[202:205], v140 offset:2048
	ds_read_b128 v[206:209], v140 offset:3072
	v_lshl_add_u64 v[140:141], s[22:23], 0, v[0:1]
	s_mov_b32 m0, s44
	v_lshl_add_u64 v[210:211], s[22:23], 0, v[130:131]
	global_load_lds_dwordx4 v[140:141], off
	s_add_i32 m0, s44, 0x2000
	s_nop 0
	global_load_lds_dwordx4 v[210:211], off
	s_barrier
	s_waitcnt lgkmcnt(0)
	s_waitcnt lgkmcnt(0)
	v_mfma_f32_16x16x32_bf16 v[118:121], v[194:197], v[162:165], v[118:121]
	v_mfma_f32_16x16x32_bf16 v[114:117], v[202:205], v[162:165], v[114:117]
	v_mfma_f32_16x16x32_bf16 v[102:105], v[194:197], v[170:173], v[102:105]
	v_mfma_f32_16x16x32_bf16 v[98:101], v[202:205], v[170:173], v[98:101]
	v_mfma_f32_16x16x32_bf16 v[86:89], v[194:197], v[178:181], v[86:89]
	v_mfma_f32_16x16x32_bf16 v[82:85], v[202:205], v[178:181], v[82:85]
	v_mfma_f32_16x16x32_bf16 v[70:73], v[194:197], v[186:189], v[70:73]
	v_mfma_f32_16x16x32_bf16 v[66:69], v[202:205], v[186:189], v[66:69]
	v_mfma_f32_16x16x32_bf16 v[118:121], v[198:201], v[166:169], v[118:121]
	v_mfma_f32_16x16x32_bf16 v[114:117], v[206:209], v[166:169], v[114:117]
	v_mfma_f32_16x16x32_bf16 v[102:105], v[198:201], v[174:177], v[102:105]
	v_mfma_f32_16x16x32_bf16 v[98:101], v[206:209], v[174:177], v[98:101]
	v_mfma_f32_16x16x32_bf16 v[86:89], v[198:201], v[182:185], v[86:89]
	v_mfma_f32_16x16x32_bf16 v[82:85], v[206:209], v[182:185], v[82:85]
	v_mfma_f32_16x16x32_bf16 v[70:73], v[198:201], v[190:193], v[70:73]
	v_mfma_f32_16x16x32_bf16 v[66:69], v[206:209], v[190:193], v[66:69]
	s_mov_b32 m0, s17
	v_lshl_add_u64 v[220:221], s[24:25], 0, v[134:135]
	s_barrier
	ds_read_b128 v[162:165], v145 offset:16384
	ds_read_b128 v[166:169], v145 offset:17408
	ds_read_b128 v[170:173], v145 offset:18432
	ds_read_b128 v[174:177], v145 offset:19456
	ds_read_b128 v[178:181], v145 offset:20480
	ds_read_b128 v[182:185], v145 offset:21504
	ds_read_b128 v[186:189], v145 offset:22528
	ds_read_b128 v[190:193], v145 offset:23552
	global_load_lds_dwordx4 v[220:221], off
	v_lshl_add_u64 v[222:223], s[24:25], 0, v[132:133]
	s_mov_b32 m0, s19
	s_nop 0
	global_load_lds_dwordx4 v[222:223], off
	s_barrier
	s_waitcnt lgkmcnt(0)
	s_waitcnt lgkmcnt(0)
	v_mfma_f32_16x16x32_bf16 v[62:65], v[146:149], v[162:165], v[62:65]
	v_mfma_f32_16x16x32_bf16 v[58:61], v[154:157], v[162:165], v[58:61]
	v_mfma_f32_16x16x32_bf16 v[46:49], v[146:149], v[170:173], v[46:49]
	v_mfma_f32_16x16x32_bf16 v[42:45], v[154:157], v[170:173], v[42:45]
	v_mfma_f32_16x16x32_bf16 v[30:33], v[146:149], v[178:181], v[30:33]
	v_mfma_f32_16x16x32_bf16 v[26:29], v[154:157], v[178:181], v[26:29]
	v_mfma_f32_16x16x32_bf16 v[14:17], v[146:149], v[186:189], v[14:17]
	v_mfma_f32_16x16x32_bf16 v[10:13], v[154:157], v[186:189], v[10:13]
	v_mfma_f32_16x16x32_bf16 v[62:65], v[150:153], v[166:169], v[62:65]
	v_mfma_f32_16x16x32_bf16 v[58:61], v[158:161], v[166:169], v[58:61]
	v_mfma_f32_16x16x32_bf16 v[46:49], v[150:153], v[174:177], v[46:49]
	v_mfma_f32_16x16x32_bf16 v[42:45], v[158:161], v[174:177], v[42:45]
	v_mfma_f32_16x16x32_bf16 v[30:33], v[150:153], v[182:185], v[30:33]
	v_mfma_f32_16x16x32_bf16 v[26:29], v[158:161], v[182:185], v[26:29]
	v_mfma_f32_16x16x32_bf16 v[14:17], v[150:153], v[190:193], v[14:17]
	v_mfma_f32_16x16x32_bf16 v[10:13], v[158:161], v[190:193], v[10:13]
	s_barrier
; #define PG8_STAGE(bufoff, gbase, voff) do { _Pragma("unroll") for (int _i = 0; _i < 2; ++_i) \
;         __builtin_amdgcn_global_load_lds((const unsigned*)((const char*)(gbase) + (voff)[_i]), (LAS unsigned*)(lds + (bufoff) + ldsw + _i * 8192), 16, 0, 0); } while (0)
; #define PG8_LDA(dst, b, h) do { _Pragma("unroll") for (int m = 0; m < 4; ++m) _Pragma("unroll") for (int k = 0; k < 2; ++k) dst[m][k] = *(const LAS bf16x8*)(lds + PG8_SA(b, h) + aoff + m * 2048 + k * 1024); } while (0)
; #define PG8_LDB(dst, b, h) do { _Pragma("unroll") for (int n = 0; n < 2; ++n) _Pragma("unroll") for (int k = 0; k < 2; ++k) dst[n][k] = *(const LAS bf16x8*)(lds + PG8_SB(b, h) + boff + n * 2048 + k * 1024); } while (0)
; #define PG8_MMA(ai, bj, At, Bt) do { __builtin_amdgcn_s_setprio(1); _Pragma("unroll") for (int m = 0; m < 4; ++m) _Pragma("unroll") for (int n = 0; n < 2; ++n) _Pragma("unroll") for (int k = 0; k < 2; ++k) \
;         acc[ai][bj][m][n] = __builtin_amdgcn_mfma_f32_16x16x32_bf16(Bt[n][k], At[m][k], acc[ai][bj][m][n], 0, 0, 0); __builtin_amdgcn_s_setprio(0); } while (0)
; #define PG8_WAIT_V(n) asm volatile("s_waitcnt vmcnt(" #n ")" ::: "memory")
; #define PG8_WAIT_L(n) asm volatile("s_waitcnt lgkmcnt(" #n ")" ::: "memory")
; #define PG8_BAR __builtin_amdgcn_s_barrier()
; #define PG8_SCHED __builtin_amdgcn_sched_barrier(0)
; template <class Epi, class Sched>
; __device__ __forceinline__ void gemm_phase(LAS unsigned char* lds, const Gemm g, const Sched& S, const Epi& E) {
;     ...
;             PG8_WAIT_V(6); PG8_BAR; PG8_MMA(1, 1, At, B1); PG8_BAR;
;             PG8_LDB(B0, 1, 0); PG8_SCHED; PG8_LDA(At, 1, 0); PG8_STAGE(PG8_SA(0, 1), a2 + hstep, voffA);
;             PG8_WAIT_L(8); PG8_BAR; PG8_WAIT_L(0); PG8_MMA(0, 0, At, B0); PG8_BAR; PG8_SCHED;
;             PG8_LDB(B1, 1, 1); PG8_STAGE(PG8_SB(1, 0), b3, voffB);
;             PG8_BAR; PG8_WAIT_L(0); PG8_MMA(0, 1, At, B1); PG8_BAR;
;             PG8_LDA(At, 1, 1); PG8_STAGE(PG8_SA(1, 0), a3, voffA);
;             PG8_BAR; PG8_WAIT_L(0); PG8_MMA(1, 0, At, B0); PG8_BAR; PG8_SCHED;
	s_add_u32 s44, s22, 0x80000
	s_addc_u32 s45, s23, 0
	s_add_i32 s46, s46, s30
	v_lshl_add_u64 v[146:147], s[44:45], 0, v[0:1]
	s_mov_b32 m0, s46
	s_nop 0
	global_load_lds_dwordx4 v[146:147], off
	v_lshl_add_u64 v[146:147], s[44:45], 0, v[130:131]
	s_add_i32 m0, s46, 0x2000
	s_nop 0
	global_load_lds_dwordx4 v[146:147], off
	s_waitcnt vmcnt(6)
	s_barrier
	v_mfma_f32_16x16x32_bf16 v[54:57], v[194:197], v[162:165], v[54:57]
	v_mfma_f32_16x16x32_bf16 v[50:53], v[202:205], v[162:165], v[50:53]
	v_mfma_f32_16x16x32_bf16 v[38:41], v[194:197], v[170:173], v[38:41]
	v_mfma_f32_16x16x32_bf16 v[34:37], v[202:205], v[170:173], v[34:37]
	v_mfma_f32_16x16x32_bf16 v[22:25], v[194:197], v[178:181], v[22:25]
	v_mfma_f32_16x16x32_bf16 v[18:21], v[202:205], v[178:181], v[18:21]
	v_mfma_f32_16x16x32_bf16 v[6:9], v[194:197], v[186:189], v[6:9]
	v_mfma_f32_16x16x32_bf16 v[2:5], v[202:205], v[186:189], v[2:5]
	v_mfma_f32_16x16x32_bf16 v[54:57], v[198:201], v[166:169], v[54:57]
	v_mfma_f32_16x16x32_bf16 v[50:53], v[206:209], v[166:169], v[50:53]
	v_mfma_f32_16x16x32_bf16 v[38:41], v[198:201], v[174:177], v[38:41]
	v_mfma_f32_16x16x32_bf16 v[34:37], v[206:209], v[174:177], v[34:37]
	v_mfma_f32_16x16x32_bf16 v[22:25], v[198:201], v[182:185], v[22:25]
	v_mfma_f32_16x16x32_bf16 v[18:21], v[206:209], v[182:185], v[18:21]
	v_mfma_f32_16x16x32_bf16 v[6:9], v[198:201], v[190:193], v[6:9]
	v_mfma_f32_16x16x32_bf16 v[2:5], v[206:209], v[190:193], v[2:5]
	s_add_i32 s44, 0, 0x18000
	v_add_u32_e32 v158, s44, v143
	s_barrier
	ds_read_b128 v[146:149], v158
	ds_read_b128 v[150:153], v158 offset:1024
	ds_read_b128 v[154:157], v158 offset:2048
	ds_read_b128 v[158:161], v158 offset:3072
	s_add_u32 s24, s24, 0x80000
	s_addc_u32 s25, s25, 0
	s_mov_b32 m0, s35
	v_lshl_add_u64 v[194:195], s[24:25], 0, v[134:135]
	ds_read_b128 v[162:165], v145 offset:32768
	ds_read_b128 v[166:169], v145 offset:33792
	ds_read_b128 v[170:173], v145 offset:34816
	ds_read_b128 v[174:177], v145 offset:35840
	ds_read_b128 v[178:181], v145 offset:36864
	ds_read_b128 v[182:185], v145 offset:37888
	ds_read_b128 v[186:189], v145 offset:38912
	ds_read_b128 v[190:193], v145 offset:39936
	global_load_lds_dwordx4 v[194:195], off
	v_lshl_add_u64 v[194:195], s[24:25], 0, v[132:133]
	s_mov_b32 m0, s36
	s_nop 0
	global_load_lds_dwordx4 v[194:195], off
	s_waitcnt lgkmcnt(8)
	s_barrier
	s_waitcnt lgkmcnt(0)
	s_waitcnt lgkmcnt(0)
	v_mfma_f32_16x16x32_bf16 v[126:129], v[146:149], v[162:165], v[126:129]
	v_mfma_f32_16x16x32_bf16 v[122:125], v[154:157], v[162:165], v[122:125]
	v_mfma_f32_16x16x32_bf16 v[110:113], v[146:149], v[170:173], v[110:113]
	v_mfma_f32_16x16x32_bf16 v[106:109], v[154:157], v[170:173], v[106:109]
	v_mfma_f32_16x16x32_bf16 v[94:97], v[146:149], v[178:181], v[94:97]
	v_mfma_f32_16x16x32_bf16 v[90:93], v[154:157], v[178:181], v[90:93]
	v_mfma_f32_16x16x32_bf16 v[78:81], v[146:149], v[186:189], v[78:81]
	v_mfma_f32_16x16x32_bf16 v[74:77], v[154:157], v[186:189], v[74:77]
	v_mfma_f32_16x16x32_bf16 v[126:129], v[150:153], v[166:169], v[126:129]
	v_mfma_f32_16x16x32_bf16 v[122:125], v[158:161], v[166:169], v[122:125]
	v_mfma_f32_16x16x32_bf16 v[110:113], v[150:153], v[174:177], v[110:113]
	v_mfma_f32_16x16x32_bf16 v[106:109], v[158:161], v[174:177], v[106:109]
	v_mfma_f32_16x16x32_bf16 v[94:97], v[150:153], v[182:185], v[94:97]
	v_mfma_f32_16x16x32_bf16 v[90:93], v[158:161], v[182:185], v[90:93]
	v_mfma_f32_16x16x32_bf16 v[78:81], v[150:153], v[190:193], v[78:81]
	v_mfma_f32_16x16x32_bf16 v[74:77], v[158:161], v[190:193], v[74:77]
	s_barrier
	s_add_i32 s24, 0, 0x1c000
	s_add_i32 s25, s44, s30
	v_add_u32_e32 v206, s24, v143
	v_lshl_add_u64 v[140:141], v[140:141], 0, s[48:49]
	s_mov_b32 m0, s25
	ds_read_b128 v[194:197], v206
	ds_read_b128 v[198:201], v206 offset:1024
	ds_read_b128 v[202:205], v206 offset:2048
	ds_read_b128 v[206:209], v206 offset:3072
	global_load_lds_dwordx4 v[140:141], off
	v_lshl_add_u64 v[140:141], v[210:211], 0, s[48:49]
	s_add_i32 m0, s25, 0x2000
	s_nop 0
	global_load_lds_dwordx4 v[140:141], off
	s_barrier
	s_waitcnt lgkmcnt(0)
	s_waitcnt lgkmcnt(0)
	v_mfma_f32_16x16x32_bf16 v[118:121], v[194:197], v[162:165], v[118:121]
	v_mfma_f32_16x16x32_bf16 v[114:117], v[202:205], v[162:165], v[114:117]
	v_mfma_f32_16x16x32_bf16 v[102:105], v[194:197], v[170:173], v[102:105]
	v_mfma_f32_16x16x32_bf16 v[98:101], v[202:205], v[170:173], v[98:101]
	v_mfma_f32_16x16x32_bf16 v[86:89], v[194:197], v[178:181], v[86:89]
	v_mfma_f32_16x16x32_bf16 v[82:85], v[202:205], v[178:181], v[82:85]
	v_mfma_f32_16x16x32_bf16 v[70:73], v[194:197], v[186:189], v[70:73]
	v_mfma_f32_16x16x32_bf16 v[66:69], v[202:205], v[186:189], v[66:69]
	v_mfma_f32_16x16x32_bf16 v[118:121], v[198:201], v[166:169], v[118:121]
	v_mfma_f32_16x16x32_bf16 v[114:117], v[206:209], v[166:169], v[114:117]
	v_mfma_f32_16x16x32_bf16 v[102:105], v[198:201], v[174:177], v[102:105]
	v_mfma_f32_16x16x32_bf16 v[98:101], v[206:209], v[174:177], v[98:101]
	v_mfma_f32_16x16x32_bf16 v[86:89], v[198:201], v[182:185], v[86:89]
	v_mfma_f32_16x16x32_bf16 v[82:85], v[206:209], v[182:185], v[82:85]
	v_mfma_f32_16x16x32_bf16 v[70:73], v[198:201], v[190:193], v[70:73]
	v_mfma_f32_16x16x32_bf16 v[66:69], v[206:209], v[190:193], v[66:69]
	s_mov_b32 m0, s37
	v_lshl_add_u64 v[140:141], v[220:221], 0, s[48:49]
	s_barrier
	ds_read_b128 v[162:165], v145 offset:49152
	ds_read_b128 v[166:169], v145 offset:50176
	ds_read_b128 v[170:173], v145 offset:51200
	ds_read_b128 v[174:177], v145 offset:52224
	ds_read_b128 v[178:181], v145 offset:53248
	ds_read_b128 v[182:185], v145 offset:54272
	ds_read_b128 v[186:189], v145 offset:55296
	ds_read_b128 v[190:193], v145 offset:56320
	global_load_lds_dwordx4 v[140:141], off
	v_lshl_add_u64 v[140:141], v[222:223], 0, s[48:49]
	s_mov_b32 m0, s38
	s_nop 0
	global_load_lds_dwordx4 v[140:141], off
	s_barrier
; __device__ __forceinline__ unsigned cvt_pk_bf16(float lo, float hi) { f32x2_t v = {lo, hi}; bf16x2_t b = __builtin_convertvector(v, bf16x2_t); return __builtin_bit_cast(unsigned, b); }
; #define PG8_STAGE(bufoff, gbase, voff) do { _Pragma("unroll") for (int _i = 0; _i < 2; ++_i) \
;         __builtin_amdgcn_global_load_lds((const unsigned*)((const char*)(gbase) + (voff)[_i]), (LAS unsigned*)(lds + (bufoff) + ldsw + _i * 8192), 16, 0, 0); } while (0)
; #define PG8_MMA(ai, bj, At, Bt) do { __builtin_amdgcn_s_setprio(1); _Pragma("unroll") for (int m = 0; m < 4; ++m) _Pragma("unroll") for (int n = 0; n < 2; ++n) _Pragma("unroll") for (int k = 0; k < 2; ++k) \
;         acc[ai][bj][m][n] = __builtin_amdgcn_mfma_f32_16x16x32_bf16(Bt[n][k], At[m][k], acc[ai][bj][m][n], 0, 0, 0); __builtin_amdgcn_s_setprio(0); } while (0)
; template <class Epi, class Sched>
; __device__ __forceinline__ void gemm_phase(LAS unsigned char* lds, const Gemm g, const Sched& S, const Epi& E) {
;     ...
;             PG8_BAR; PG8_WAIT_L(0); PG8_MMA(1, 0, At, B0); PG8_BAR; PG8_SCHED;
;             PG8_STAGE(PG8_SB(1, 1), b3 + hstep, voffB);
;             PG8_WAIT_V(6); PG8_BAR; PG8_MMA(1, 1, At, B1); PG8_BAR;
;     __device__ __forceinline__ void operator()(const f32x4 (&acc)[2][2][4][2], const pg8::Unit& u, int wr, int wc, int fr, int fq) const {
;         const int row0 = u.pm * 256 + wr * 64 + fr; const int col0 = u.pn * 256 + wc * 32 + 8 * fq;
; #pragma unroll
;         for (int ai = 0; ai < 2; ++ai)
; #pragma unroll
;             for (int m = 0; m < 4; ++m) { const int row = row0 + ai * 128 + m * 16; bf16_t* rowp = O + (size_t)row * ldc + col0;
; #pragma unroll
;                 for (int bj = 0; bj < 2; ++bj) { f32x4 v0 = acc[ai][bj][m][0], v1 = acc[ai][bj][m][1];
;                     if (ACT == 1) {
; #pragma unroll
;                         for (int j = 0; j < 4; ++j) { float a = fmaxf(v0[j], 0.f), b = fmaxf(v1[j], 0.f); v0[j] = a * a; v1[j] = b * b; } }
;                     if (ACT == 0) { if (u.pn == (C_G / 256) && bj == 0 && wc == 0 && fq < 2) { float* gp = gate + (size_t)row * 16 + 8 * fq; *(f32x4*)gp = v0; *(f32x4*)(gp + 4) = v1; } }
;                     u32x4 w; w.x = cvt_pk_bf16(v0[0], v0[1]); w.y = cvt_pk_bf16(v0[2], v0[3]); w.z = cvt_pk_bf16(v1[0], v1[1]); w.w = cvt_pk_bf16(v1[2], v1[3]);
;                     *(u32x4*)(rowp + bj * 128) = w; } }
	s_waitcnt lgkmcnt(0)
	s_waitcnt lgkmcnt(0)
	v_mfma_f32_16x16x32_bf16 v[62:65], v[146:149], v[162:165], v[62:65]
	v_mfma_f32_16x16x32_bf16 v[58:61], v[154:157], v[162:165], v[58:61]
	v_mfma_f32_16x16x32_bf16 v[46:49], v[146:149], v[170:173], v[46:49]
	v_mfma_f32_16x16x32_bf16 v[42:45], v[154:157], v[170:173], v[42:45]
	v_mfma_f32_16x16x32_bf16 v[30:33], v[146:149], v[178:181], v[30:33]
	v_mfma_f32_16x16x32_bf16 v[26:29], v[154:157], v[178:181], v[26:29]
	v_mfma_f32_16x16x32_bf16 v[14:17], v[146:149], v[186:189], v[14:17]
	v_mfma_f32_16x16x32_bf16 v[10:13], v[154:157], v[186:189], v[10:13]
	v_mfma_f32_16x16x32_bf16 v[62:65], v[150:153], v[166:169], v[62:65]
	v_mfma_f32_16x16x32_bf16 v[58:61], v[158:161], v[166:169], v[58:61]
	v_mfma_f32_16x16x32_bf16 v[46:49], v[150:153], v[174:177], v[46:49]
	v_mfma_f32_16x16x32_bf16 v[42:45], v[158:161], v[174:177], v[42:45]
	v_mfma_f32_16x16x32_bf16 v[30:33], v[150:153], v[182:185], v[30:33]
	v_mfma_f32_16x16x32_bf16 v[26:29], v[158:161], v[182:185], v[26:29]
	v_mfma_f32_16x16x32_bf16 v[14:17], v[150:153], v[190:193], v[14:17]
	v_mfma_f32_16x16x32_bf16 v[10:13], v[158:161], v[190:193], v[10:13]
	s_barrier
	s_add_u32 s22, s22, 0x80080
	s_addc_u32 s23, s23, 0
	s_add_i32 s24, s24, s30
	v_lshl_add_u64 v[140:141], s[22:23], 0, v[0:1]
	s_mov_b32 m0, s24
	s_nop 0
	global_load_lds_dwordx4 v[140:141], off
	v_lshl_add_u64 v[140:141], s[22:23], 0, v[130:131]
	s_add_i32 m0, s24, 0x2000
	s_nop 0
	global_load_lds_dwordx4 v[140:141], off
	s_waitcnt vmcnt(6)
	s_barrier
	v_mfma_f32_16x16x32_bf16 v[54:57], v[194:197], v[162:165], v[54:57]
	v_mfma_f32_16x16x32_bf16 v[50:53], v[202:205], v[162:165], v[50:53]
	v_mfma_f32_16x16x32_bf16 v[38:41], v[194:197], v[170:173], v[38:41]
	v_mfma_f32_16x16x32_bf16 v[34:37], v[202:205], v[170:173], v[34:37]
	v_mfma_f32_16x16x32_bf16 v[22:25], v[194:197], v[178:181], v[22:25]
	v_mfma_f32_16x16x32_bf16 v[18:21], v[202:205], v[178:181], v[18:21]
	v_mfma_f32_16x16x32_bf16 v[6:9], v[194:197], v[186:189], v[6:9]
	v_mfma_f32_16x16x32_bf16 v[2:5], v[202:205], v[186:189], v[2:5]
	v_mfma_f32_16x16x32_bf16 v[54:57], v[198:201], v[166:169], v[54:57]
	v_mfma_f32_16x16x32_bf16 v[50:53], v[206:209], v[166:169], v[50:53]
	v_mfma_f32_16x16x32_bf16 v[38:41], v[198:201], v[174:177], v[38:41]
	v_mfma_f32_16x16x32_bf16 v[34:37], v[206:209], v[174:177], v[34:37]
	v_mfma_f32_16x16x32_bf16 v[22:25], v[198:201], v[182:185], v[22:25]
	v_mfma_f32_16x16x32_bf16 v[18:21], v[206:209], v[182:185], v[18:21]
	v_mfma_f32_16x16x32_bf16 v[6:9], v[198:201], v[190:193], v[6:9]
	v_mfma_f32_16x16x32_bf16 v[2:5], v[206:209], v[190:193], v[2:5]
	s_add_i32 s43, s43, 2
	s_add_u32 s20, s20, 0x100
	s_addc_u32 s21, s21, 0
	s_add_u32 s41, s41, 0x100
	s_addc_u32 s42, s42, 0
	s_cmp_gt_u32 s43, 29
	s_barrier
	s_cbranch_scc0 .LBB0_1279
	v_lshl_add_u32 v146, s18, 8, v142
	v_lshl_or_b32 v140, s16, 8, v144
	v_ashrrev_i32_e32 v147, 31, v146
	v_ashrrev_i32_e32 v141, 31, v140
	v_lshlrev_b64 v[148:149], 14, v[146:147]
	v_max_f32_e32 v122, v122, v122
	v_max_f32_e32 v123, v123, v123
	v_lshl_add_u64 v[148:149], s[58:59], 0, v[148:149]
	v_lshlrev_b64 v[150:151], 1, v[140:141]
	v_max_f32_e32 v122, 0, v122
	v_max_f32_e32 v123, 0, v123
	v_lshl_add_u64 v[140:141], v[148:149], 0, v[150:151]
	v_pk_mul_f32 v[148:149], v[122:123], v[122:123]
	v_max_f32_e32 v123, v124, v124
	v_max_f32_e32 v126, v126, v126
	v_max_f32_e32 v127, v127, v127
	v_max_f32_e32 v122, v128, v128
	v_max_f32_e32 v124, 0, v123
	v_max_f32_e32 v123, v129, v129
	v_max_f32_e32 v125, v125, v125
	v_max_f32_e32 v126, 0, v126
	v_max_f32_e32 v127, 0, v127
	v_max_f32_e32 v122, 0, v122
	v_max_f32_e32 v123, 0, v123
	v_max_f32_e32 v125, 0, v125
	v_pk_mul_f32 v[126:127], v[126:127], v[126:127]
	v_pk_mul_f32 v[128:129], v[122:123], v[122:123]
	v_pk_mul_f32 v[152:153], v[124:125], v[124:125]
	v_max_f32_e32 v114, v114, v114
	v_max_f32_e32 v115, v115, v115
	v_cvt_pk_bf16_f32 v122, v126, v127
	v_cvt_pk_bf16_f32 v123, v128, v129
	v_cvt_pk_bf16_f32 v124, v148, v149
	v_cvt_pk_bf16_f32 v125, v152, v153
	v_max_f32_e32 v114, 0, v114
	v_max_f32_e32 v115, 0, v115
	global_store_dwordx4 v[140:141], v[122:125], off
	v_max_f32_e32 v118, v118, v118
	v_max_f32_e32 v119, v119, v119
	v_pk_mul_f32 v[122:123], v[114:115], v[114:115]
	v_max_f32_e32 v115, v116, v116
	v_max_f32_e32 v114, v120, v120
	v_max_f32_e32 v116, 0, v115
	v_max_f32_e32 v115, v121, v121
	v_max_f32_e32 v117, v117, v117
	v_max_f32_e32 v118, 0, v118
	v_max_f32_e32 v119, 0, v119
	v_max_f32_e32 v114, 0, v114
	v_max_f32_e32 v115, 0, v115
	v_max_f32_e32 v117, 0, v117
	v_pk_mul_f32 v[118:119], v[118:119], v[118:119]
	v_pk_mul_f32 v[120:121], v[114:115], v[114:115]
	v_pk_mul_f32 v[124:125], v[116:117], v[116:117]
	v_max_f32_e32 v106, v106, v106
	v_max_f32_e32 v107, v107, v107
	v_cvt_pk_bf16_f32 v114, v118, v119
	v_cvt_pk_bf16_f32 v115, v120, v121
	v_cvt_pk_bf16_f32 v116, v122, v123
	v_cvt_pk_bf16_f32 v117, v124, v125
	v_max_f32_e32 v106, 0, v106
	v_max_f32_e32 v107, 0, v107
	global_store_dwordx4 v[140:141], v[114:117], off offset:256
	v_max_f32_e32 v110, v110, v110
	v_max_f32_e32 v111, v111, v111
	v_or_b32_e32 v114, 16, v146
	v_pk_mul_f32 v[116:117], v[106:107], v[106:107]
	v_max_f32_e32 v107, v108, v108
	v_ashrrev_i32_e32 v115, 31, v114
	v_max_f32_e32 v106, v112, v112
	v_max_f32_e32 v108, 0, v107
	v_max_f32_e32 v107, v113, v113
	v_max_f32_e32 v109, v109, v109
	v_lshlrev_b64 v[114:115], 14, v[114:115]
	v_max_f32_e32 v110, 0, v110
	v_max_f32_e32 v111, 0, v111
	v_max_f32_e32 v106, 0, v106
	v_max_f32_e32 v107, 0, v107
	v_max_f32_e32 v109, 0, v109
	v_lshl_add_u64 v[114:115], s[58:59], 0, v[114:115]
	v_pk_mul_f32 v[110:111], v[110:111], v[110:111]
; __device__ __forceinline__ unsigned cvt_pk_bf16(float lo, float hi) { f32x2_t v = {lo, hi}; bf16x2_t b = __builtin_convertvector(v, bf16x2_t); return __builtin_bit_cast(unsigned, b); }
;     __device__ __forceinline__ void operator()(const f32x4 (&acc)[2][2][4][2], const pg8::Unit& u, int wr, int wc, int fr, int fq) const {
;         const int row0 = u.pm * 256 + wr * 64 + fr; const int col0 = u.pn * 256 + wc * 32 + 8 * fq;
; #pragma unroll
;         for (int ai = 0; ai < 2; ++ai)
; #pragma unroll
;             for (int m = 0; m < 4; ++m) { const int row = row0 + ai * 128 + m * 16; bf16_t* rowp = O + (size_t)row * ldc + col0;
; #pragma unroll
;                 for (int bj = 0; bj < 2; ++bj) { f32x4 v0 = acc[ai][bj][m][0], v1 = acc[ai][bj][m][1];
;                     if (ACT == 1) {
; #pragma unroll
;                         for (int j = 0; j < 4; ++j) { float a = fmaxf(v0[j], 0.f), b = fmaxf(v1[j], 0.f); v0[j] = a * a; v1[j] = b * b; } }
;                     if (ACT == 0) { if (u.pn == (C_G / 256) && bj == 0 && wc == 0 && fq < 2) { float* gp = gate + (size_t)row * 16 + 8 * fq; *(f32x4*)gp = v0; *(f32x4*)(gp + 4) = v1; } }
;                     u32x4 w; w.x = cvt_pk_bf16(v0[0], v0[1]); w.y = cvt_pk_bf16(v0[2], v0[3]); w.z = cvt_pk_bf16(v1[0], v1[1]); w.w = cvt_pk_bf16(v1[2], v1[3]);
;                     *(u32x4*)(rowp + bj * 128) = w; } }
	v_pk_mul_f32 v[112:113], v[106:107], v[106:107]
	v_pk_mul_f32 v[118:119], v[108:109], v[108:109]
	v_max_f32_e32 v98, v98, v98
	v_max_f32_e32 v99, v99, v99
	v_lshl_add_u64 v[114:115], v[114:115], 0, v[150:151]
	v_cvt_pk_bf16_f32 v106, v110, v111
	v_cvt_pk_bf16_f32 v107, v112, v113
	v_cvt_pk_bf16_f32 v108, v116, v117
	v_cvt_pk_bf16_f32 v109, v118, v119
	v_max_f32_e32 v98, 0, v98
	v_max_f32_e32 v99, 0, v99
	global_store_dwordx4 v[114:115], v[106:109], off
	v_max_f32_e32 v102, v102, v102
	v_max_f32_e32 v103, v103, v103
	v_pk_mul_f32 v[106:107], v[98:99], v[98:99]
	v_max_f32_e32 v99, v100, v100
	v_max_f32_e32 v98, v104, v104
	v_max_f32_e32 v100, 0, v99
	v_max_f32_e32 v99, v105, v105
	v_max_f32_e32 v101, v101, v101
	v_max_f32_e32 v102, 0, v102
	v_max_f32_e32 v103, 0, v103
	v_max_f32_e32 v98, 0, v98
	v_max_f32_e32 v99, 0, v99
	v_max_f32_e32 v101, 0, v101
	v_pk_mul_f32 v[102:103], v[102:103], v[102:103]
	v_pk_mul_f32 v[104:105], v[98:99], v[98:99]
	v_pk_mul_f32 v[108:109], v[100:101], v[100:101]
	v_max_f32_e32 v90, v90, v90
	v_max_f32_e32 v91, v91, v91
	v_cvt_pk_bf16_f32 v98, v102, v103
	v_cvt_pk_bf16_f32 v99, v104, v105
	v_cvt_pk_bf16_f32 v100, v106, v107
	v_cvt_pk_bf16_f32 v101, v108, v109
	v_max_f32_e32 v90, 0, v90
	v_max_f32_e32 v91, 0, v91
	global_store_dwordx4 v[114:115], v[98:101], off offset:256
	v_max_f32_e32 v94, v94, v94
	v_max_f32_e32 v95, v95, v95
	v_or_b32_e32 v98, 32, v146
	v_pk_mul_f32 v[100:101], v[90:91], v[90:91]
	v_max_f32_e32 v91, v92, v92
	v_ashrrev_i32_e32 v99, 31, v98
	v_max_f32_e32 v90, v96, v96
	v_max_f32_e32 v92, 0, v91
	v_max_f32_e32 v91, v97, v97
	v_max_f32_e32 v93, v93, v93
	v_lshlrev_b64 v[98:99], 14, v[98:99]
	v_max_f32_e32 v94, 0, v94
	v_max_f32_e32 v95, 0, v95
	v_max_f32_e32 v90, 0, v90
	v_max_f32_e32 v91, 0, v91
	v_max_f32_e32 v93, 0, v93
	v_lshl_add_u64 v[98:99], s[58:59], 0, v[98:99]
	v_pk_mul_f32 v[94:95], v[94:95], v[94:95]
	v_pk_mul_f32 v[96:97], v[90:91], v[90:91]
	v_pk_mul_f32 v[102:103], v[92:93], v[92:93]
	v_max_f32_e32 v82, v82, v82
	v_max_f32_e32 v83, v83, v83
	v_lshl_add_u64 v[98:99], v[98:99], 0, v[150:151]
	v_cvt_pk_bf16_f32 v90, v94, v95
	v_cvt_pk_bf16_f32 v91, v96, v97
	v_cvt_pk_bf16_f32 v92, v100, v101
	v_cvt_pk_bf16_f32 v93, v102, v103
	v_max_f32_e32 v82, 0, v82
	v_max_f32_e32 v83, 0, v83
	global_store_dwordx4 v[98:99], v[90:93], off
	v_max_f32_e32 v86, v86, v86
	v_max_f32_e32 v87, v87, v87
	v_pk_mul_f32 v[90:91], v[82:83], v[82:83]
	v_max_f32_e32 v83, v84, v84
	v_max_f32_e32 v82, v88, v88
	v_max_f32_e32 v84, 0, v83
	v_max_f32_e32 v83, v89, v89
	v_max_f32_e32 v85, v85, v85
	v_max_f32_e32 v86, 0, v86
	v_max_f32_e32 v87, 0, v87
	v_max_f32_e32 v82, 0, v82
	v_max_f32_e32 v83, 0, v83
	v_max_f32_e32 v85, 0, v85
	v_pk_mul_f32 v[86:87], v[86:87], v[86:87]
	v_pk_mul_f32 v[88:89], v[82:83], v[82:83]
	v_pk_mul_f32 v[92:93], v[84:85], v[84:85]
	v_max_f32_e32 v74, v74, v74
	v_max_f32_e32 v75, v75, v75
	v_cvt_pk_bf16_f32 v82, v86, v87
	v_cvt_pk_bf16_f32 v83, v88, v89
	v_cvt_pk_bf16_f32 v84, v90, v91
	v_cvt_pk_bf16_f32 v85, v92, v93
	v_max_f32_e32 v74, 0, v74
	v_max_f32_e32 v75, 0, v75
	global_store_dwordx4 v[98:99], v[82:85], off offset:256
	v_max_f32_e32 v78, v78, v78
	v_max_f32_e32 v79, v79, v79
	v_or_b32_e32 v82, 48, v146
	v_pk_mul_f32 v[84:85], v[74:75], v[74:75]
	v_max_f32_e32 v75, v76, v76
	v_ashrrev_i32_e32 v83, 31, v82
	v_max_f32_e32 v74, v80, v80
	v_max_f32_e32 v76, 0, v75
	v_max_f32_e32 v75, v81, v81
	v_max_f32_e32 v77, v77, v77
	v_lshlrev_b64 v[82:83], 14, v[82:83]
	v_max_f32_e32 v78, 0, v78
	v_max_f32_e32 v79, 0, v79
	v_max_f32_e32 v74, 0, v74
	v_max_f32_e32 v75, 0, v75
	v_max_f32_e32 v77, 0, v77
	v_lshl_add_u64 v[82:83], s[58:59], 0, v[82:83]
	v_pk_mul_f32 v[78:79], v[78:79], v[78:79]
	v_pk_mul_f32 v[80:81], v[74:75], v[74:75]
	v_pk_mul_f32 v[86:87], v[76:77], v[76:77]
	v_max_f32_e32 v66, v66, v66
	v_max_f32_e32 v67, v67, v67
	v_lshl_add_u64 v[82:83], v[82:83], 0, v[150:151]
	v_cvt_pk_bf16_f32 v74, v78, v79
	v_cvt_pk_bf16_f32 v75, v80, v81
	v_cvt_pk_bf16_f32 v76, v84, v85
	v_cvt_pk_bf16_f32 v77, v86, v87
	v_max_f32_e32 v66, 0, v66
	v_max_f32_e32 v67, 0, v67
	global_store_dwordx4 v[82:83], v[74:77], off
	v_max_f32_e32 v70, v70, v70
	v_max_f32_e32 v71, v71, v71
	v_pk_mul_f32 v[74:75], v[66:67], v[66:67]
	v_max_f32_e32 v67, v68, v68
	v_max_f32_e32 v66, v72, v72
	v_max_f32_e32 v68, 0, v67
	v_max_f32_e32 v67, v73, v73
	v_max_f32_e32 v69, v69, v69
	v_max_f32_e32 v70, 0, v70
	v_max_f32_e32 v71, 0, v71
	v_max_f32_e32 v66, 0, v66
	v_max_f32_e32 v67, 0, v67
	v_max_f32_e32 v69, 0, v69
	v_pk_mul_f32 v[70:71], v[70:71], v[70:71]
	v_pk_mul_f32 v[72:73], v[66:67], v[66:67]
	v_pk_mul_f32 v[76:77], v[68:69], v[68:69]
	v_max_f32_e32 v58, v58, v58
	v_max_f32_e32 v59, v59, v59
	v_cvt_pk_bf16_f32 v66, v70, v71
	v_cvt_pk_bf16_f32 v67, v72, v73
	v_cvt_pk_bf16_f32 v68, v74, v75
	v_cvt_pk_bf16_f32 v69, v76, v77
	v_max_f32_e32 v58, 0, v58
	v_max_f32_e32 v59, 0, v59
	global_store_dwordx4 v[82:83], v[66:69], off offset:256
	v_max_f32_e32 v62, v62, v62
	v_max_f32_e32 v63, v63, v63
	v_pk_mul_f32 v[68:69], v[58:59], v[58:59]
	v_max_f32_e32 v59, v60, v60
	v_max_f32_e32 v62, 0, v62
	v_max_f32_e32 v63, 0, v63
	v_max_f32_e32 v58, v64, v64
	v_max_f32_e32 v60, 0, v59
	v_max_f32_e32 v59, v65, v65
	v_max_f32_e32 v61, v61, v61
	v_pk_mul_f32 v[62:63], v[62:63], v[62:63]
	v_max_f32_e32 v58, 0, v58
	v_max_f32_e32 v59, 0, v59
	v_max_f32_e32 v61, 0, v61
	s_mov_b32 s3, 0x200000
	v_pk_mul_f32 v[64:65], v[58:59], v[58:59]
	v_pk_mul_f32 v[70:71], v[60:61], v[60:61]
	v_cvt_pk_bf16_f32 v58, v62, v63
	v_add_co_u32_e32 v62, vcc, s3, v140
	v_max_f32_e32 v50, v50, v50
	v_max_f32_e32 v51, v51, v51
	v_cvt_pk_bf16_f32 v59, v64, v65
; __device__ __forceinline__ unsigned cvt_pk_bf16(float lo, float hi) { f32x2_t v = {lo, hi}; bf16x2_t b = __builtin_convertvector(v, bf16x2_t); return __builtin_bit_cast(unsigned, b); }
; #define PG8_WAIT_V(n) asm volatile("s_waitcnt vmcnt(" #n ")" ::: "memory")
; #define PG8_BAR __builtin_amdgcn_s_barrier()
; template <class Epi, class Sched>
; __device__ __forceinline__ void gemm_phase(LAS unsigned char* lds, const Gemm g, const Sched& S, const Epi& E) {
;     ...
;         E(acc, cur, wr, wc, fr, fq); S.done(cur);
;         if (!has_next) break;
; #pragma unroll
;         for (int a = 0; a < 2; ++a)
; #pragma unroll
;             for (int b = 0; b < 2; ++b)
; #pragma unroll
;                 for (int m = 0; m < 4; ++m)
; #pragma unroll
;                     for (int n = 0; n < 2; ++n) acc[a][b][m][n] = (f32x4){0.f, 0.f, 0.f, 0.f};
;         cur = nxt; cA = nA; cB = nB; ++ui;
;     }
;     PG8_WAIT_V(0);
;     if (wr == 0) PG8_BAR;
;     __device__ __forceinline__ void operator()(const f32x4 (&acc)[2][2][4][2], const pg8::Unit& u, int wr, int wc, int fr, int fq) const {
;         const int row0 = u.pm * 256 + wr * 64 + fr; const int col0 = u.pn * 256 + wc * 32 + 8 * fq;
; #pragma unroll
;         for (int ai = 0; ai < 2; ++ai)
; #pragma unroll
;             for (int m = 0; m < 4; ++m) { const int row = row0 + ai * 128 + m * 16; bf16_t* rowp = O + (size_t)row * ldc + col0;
; #pragma unroll
;                 for (int bj = 0; bj < 2; ++bj) { f32x4 v0 = acc[ai][bj][m][0], v1 = acc[ai][bj][m][1];
;                     if (ACT == 1) {
; #pragma unroll
;                         for (int j = 0; j < 4; ++j) { float a = fmaxf(v0[j], 0.f), b = fmaxf(v1[j], 0.f); v0[j] = a * a; v1[j] = b * b; } }
;                     if (ACT == 0) { if (u.pn == (C_G / 256) && bj == 0 && wc == 0 && fq < 2) { float* gp = gate + (size_t)row * 16 + 8 * fq; *(f32x4*)gp = v0; *(f32x4*)(gp + 4) = v1; } }
;                     u32x4 w; w.x = cvt_pk_bf16(v0[0], v0[1]); w.y = cvt_pk_bf16(v0[2], v0[3]); w.z = cvt_pk_bf16(v1[0], v1[1]); w.w = cvt_pk_bf16(v1[2], v1[3]);
;                     *(u32x4*)(rowp + bj * 128) = w; } }
	v_cvt_pk_bf16_f32 v60, v68, v69
	v_cvt_pk_bf16_f32 v61, v70, v71
	v_addc_co_u32_e32 v63, vcc, 0, v141, vcc
	v_max_f32_e32 v50, 0, v50
	v_max_f32_e32 v51, 0, v51
	global_store_dwordx4 v[62:63], v[58:61], off
	v_max_f32_e32 v54, v54, v54
	v_max_f32_e32 v55, v55, v55
	v_pk_mul_f32 v[58:59], v[50:51], v[50:51]
	v_max_f32_e32 v51, v52, v52
	v_max_f32_e32 v50, v56, v56
	v_max_f32_e32 v52, 0, v51
	v_max_f32_e32 v51, v57, v57
	v_max_f32_e32 v53, v53, v53
	v_max_f32_e32 v54, 0, v54
	v_max_f32_e32 v55, 0, v55
	v_max_f32_e32 v50, 0, v50
	v_max_f32_e32 v51, 0, v51
	v_max_f32_e32 v53, 0, v53
	s_mov_b64 s[20:21], 0x200000
	v_pk_mul_f32 v[54:55], v[54:55], v[54:55]
	v_pk_mul_f32 v[56:57], v[50:51], v[50:51]
	v_pk_mul_f32 v[60:61], v[52:53], v[52:53]
	v_max_f32_e32 v42, v42, v42
	v_max_f32_e32 v43, v43, v43
	v_lshl_add_u64 v[66:67], v[140:141], 0, s[20:21]
	v_cvt_pk_bf16_f32 v50, v54, v55
	v_cvt_pk_bf16_f32 v51, v56, v57
	v_cvt_pk_bf16_f32 v52, v58, v59
	v_cvt_pk_bf16_f32 v53, v60, v61
	v_max_f32_e32 v42, 0, v42
	v_max_f32_e32 v43, 0, v43
	global_store_dwordx4 v[66:67], v[50:53], off offset:256
	v_max_f32_e32 v46, v46, v46
	v_max_f32_e32 v47, v47, v47
	v_pk_mul_f32 v[52:53], v[42:43], v[42:43]
	v_max_f32_e32 v43, v44, v44
	v_max_f32_e32 v46, 0, v46
	v_max_f32_e32 v47, 0, v47
	v_max_f32_e32 v42, v48, v48
	v_max_f32_e32 v44, 0, v43
	v_max_f32_e32 v43, v49, v49
	v_max_f32_e32 v45, v45, v45
	v_pk_mul_f32 v[46:47], v[46:47], v[46:47]
	v_max_f32_e32 v42, 0, v42
	v_max_f32_e32 v43, 0, v43
	v_max_f32_e32 v45, 0, v45
	s_mov_b32 s3, 0x240000
	v_pk_mul_f32 v[48:49], v[42:43], v[42:43]
	v_pk_mul_f32 v[54:55], v[44:45], v[44:45]
	v_cvt_pk_bf16_f32 v42, v46, v47
	v_add_co_u32_e32 v46, vcc, s3, v140
	v_max_f32_e32 v34, v34, v34
	v_max_f32_e32 v35, v35, v35
	v_cvt_pk_bf16_f32 v43, v48, v49
	v_cvt_pk_bf16_f32 v44, v52, v53
	v_cvt_pk_bf16_f32 v45, v54, v55
	v_addc_co_u32_e32 v47, vcc, 0, v141, vcc
	v_max_f32_e32 v34, 0, v34
	v_max_f32_e32 v35, 0, v35
	global_store_dwordx4 v[46:47], v[42:45], off
	v_max_f32_e32 v38, v38, v38
	v_max_f32_e32 v39, v39, v39
	v_pk_mul_f32 v[42:43], v[34:35], v[34:35]
	v_max_f32_e32 v35, v36, v36
	v_max_f32_e32 v34, v40, v40
	v_max_f32_e32 v36, 0, v35
	v_max_f32_e32 v35, v41, v41
	v_max_f32_e32 v37, v37, v37
	v_max_f32_e32 v38, 0, v38
	v_max_f32_e32 v39, 0, v39
	v_max_f32_e32 v34, 0, v34
	v_max_f32_e32 v35, 0, v35
	v_max_f32_e32 v37, 0, v37
	s_mov_b64 s[20:21], 0x240000
	v_pk_mul_f32 v[38:39], v[38:39], v[38:39]
	v_pk_mul_f32 v[40:41], v[34:35], v[34:35]
	v_pk_mul_f32 v[44:45], v[36:37], v[36:37]
	v_max_f32_e32 v26, v26, v26
	v_max_f32_e32 v27, v27, v27
	v_lshl_add_u64 v[50:51], v[140:141], 0, s[20:21]
	v_cvt_pk_bf16_f32 v34, v38, v39
	v_cvt_pk_bf16_f32 v35, v40, v41
	v_cvt_pk_bf16_f32 v36, v42, v43
	v_cvt_pk_bf16_f32 v37, v44, v45
	v_max_f32_e32 v26, 0, v26
	v_max_f32_e32 v27, 0, v27
	global_store_dwordx4 v[50:51], v[34:37], off offset:256
	v_max_f32_e32 v30, v30, v30
	v_max_f32_e32 v31, v31, v31
	v_pk_mul_f32 v[36:37], v[26:27], v[26:27]
	v_max_f32_e32 v27, v28, v28
	v_max_f32_e32 v30, 0, v30
	v_max_f32_e32 v31, 0, v31
	v_max_f32_e32 v26, v32, v32
	v_max_f32_e32 v28, 0, v27
	v_max_f32_e32 v27, v33, v33
	v_max_f32_e32 v29, v29, v29
	v_pk_mul_f32 v[30:31], v[30:31], v[30:31]
	v_max_f32_e32 v26, 0, v26
	v_max_f32_e32 v27, 0, v27
	v_max_f32_e32 v29, 0, v29
	s_mov_b32 s3, 0x280000
	v_pk_mul_f32 v[32:33], v[26:27], v[26:27]
	v_pk_mul_f32 v[38:39], v[28:29], v[28:29]
	v_cvt_pk_bf16_f32 v26, v30, v31
	v_add_co_u32_e32 v30, vcc, s3, v140
	v_max_f32_e32 v18, v18, v18
	v_max_f32_e32 v19, v19, v19
	v_cvt_pk_bf16_f32 v27, v32, v33
	v_cvt_pk_bf16_f32 v28, v36, v37
	v_cvt_pk_bf16_f32 v29, v38, v39
	v_addc_co_u32_e32 v31, vcc, 0, v141, vcc
	v_max_f32_e32 v18, 0, v18
	v_max_f32_e32 v19, 0, v19
	global_store_dwordx4 v[30:31], v[26:29], off
	v_max_f32_e32 v22, v22, v22
	v_max_f32_e32 v23, v23, v23
	v_pk_mul_f32 v[26:27], v[18:19], v[18:19]
	v_max_f32_e32 v19, v20, v20
	v_max_f32_e32 v18, v24, v24
	v_max_f32_e32 v20, 0, v19
	v_max_f32_e32 v19, v25, v25
	v_max_f32_e32 v21, v21, v21
	v_max_f32_e32 v22, 0, v22
	v_max_f32_e32 v23, 0, v23
	v_max_f32_e32 v18, 0, v18
	v_max_f32_e32 v19, 0, v19
	v_max_f32_e32 v21, 0, v21
	s_mov_b64 s[20:21], 0x280000
	v_pk_mul_f32 v[22:23], v[22:23], v[22:23]
	v_pk_mul_f32 v[24:25], v[18:19], v[18:19]
	v_pk_mul_f32 v[28:29], v[20:21], v[20:21]
	v_max_f32_e32 v10, v10, v10
	v_max_f32_e32 v11, v11, v11
	v_lshl_add_u64 v[34:35], v[140:141], 0, s[20:21]
	v_cvt_pk_bf16_f32 v18, v22, v23
	v_cvt_pk_bf16_f32 v19, v24, v25
	v_cvt_pk_bf16_f32 v20, v26, v27
	v_cvt_pk_bf16_f32 v21, v28, v29
	v_max_f32_e32 v10, 0, v10
	v_max_f32_e32 v11, 0, v11
	global_store_dwordx4 v[34:35], v[18:21], off offset:256
	v_max_f32_e32 v14, v14, v14
	v_max_f32_e32 v15, v15, v15
	v_pk_mul_f32 v[20:21], v[10:11], v[10:11]
	v_max_f32_e32 v11, v12, v12
	v_max_f32_e32 v14, 0, v14
	v_max_f32_e32 v15, 0, v15
	v_max_f32_e32 v10, v16, v16
	v_max_f32_e32 v12, 0, v11
	v_max_f32_e32 v11, v17, v17
	v_max_f32_e32 v13, v13, v13
	v_pk_mul_f32 v[14:15], v[14:15], v[14:15]
	v_max_f32_e32 v10, 0, v10
	v_max_f32_e32 v11, 0, v11
	v_max_f32_e32 v13, 0, v13
	s_mov_b32 s3, 0x2c0000
	v_pk_mul_f32 v[16:17], v[10:11], v[10:11]
	v_pk_mul_f32 v[22:23], v[12:13], v[12:13]
	v_cvt_pk_bf16_f32 v10, v14, v15
	v_add_co_u32_e32 v14, vcc, s3, v140
	v_max_f32_e32 v2, v2, v2
	v_max_f32_e32 v3, v3, v3
	v_cvt_pk_bf16_f32 v11, v16, v17
	v_cvt_pk_bf16_f32 v12, v20, v21
	v_cvt_pk_bf16_f32 v13, v22, v23
	v_addc_co_u32_e32 v15, vcc, 0, v141, vcc
	v_max_f32_e32 v2, 0, v2
	v_max_f32_e32 v3, 0, v3
	global_store_dwordx4 v[14:15], v[10:13], off
	v_max_f32_e32 v6, v6, v6
	v_max_f32_e32 v7, v7, v7
	v_pk_mul_f32 v[10:11], v[2:3], v[2:3]
	v_max_f32_e32 v3, v4, v4
	v_max_f32_e32 v2, v8, v8
	v_max_f32_e32 v4, 0, v3
	v_max_f32_e32 v3, v9, v9
	v_max_f32_e32 v5, v5, v5
	v_max_f32_e32 v6, 0, v6
	v_max_f32_e32 v7, 0, v7
	v_max_f32_e32 v2, 0, v2
	v_max_f32_e32 v3, 0, v3
	v_max_f32_e32 v5, 0, v5
	s_mov_b64 s[20:21], 0x2c0000
	v_pk_mul_f32 v[6:7], v[6:7], v[6:7]
	v_pk_mul_f32 v[8:9], v[2:3], v[2:3]
	v_pk_mul_f32 v[12:13], v[4:5], v[4:5]
	v_lshl_add_u64 v[18:19], v[140:141], 0, s[20:21]
	v_cvt_pk_bf16_f32 v2, v6, v7
	v_cvt_pk_bf16_f32 v3, v8, v9
	v_cvt_pk_bf16_f32 v4, v10, v11
	v_cvt_pk_bf16_f32 v5, v12, v13
	s_and_b64 vcc, exec, s[0:1]
	s_mov_b32 s16, s8
	s_mov_b32 s18, s10
	s_mov_b64 s[22:23], s[14:15]
	s_mov_b64 s[20:21], s[12:13]
	global_store_dwordx4 v[18:19], v[2:5], off offset:256
	s_cbranch_vccz .LBB0_1276
	s_waitcnt vmcnt(0)
	s_cmpk_gt_u32 s27, 0xff
	s_cbranch_scc1 .LBB0_1283
	s_barrier

; #define PG8_STAGE(bufoff, gbase, voff) do { _Pragma("unroll") for (int _i = 0; _i < 2; ++_i) \
;         __builtin_amdgcn_global_load_lds((const unsigned*)((const char*)(gbase) + (voff)[_i]), (LAS unsigned*)(lds + (bufoff) + ldsw + _i * 8192), 16, 0, 0); } while (0)
; #define PG8_LDA(dst, b, h) do { _Pragma("unroll") for (int m = 0; m < 4; ++m) _Pragma("unroll") for (int k = 0; k < 2; ++k) dst[m][k] = *(const LAS bf16x8*)(lds + PG8_SA(b, h) + aoff + m * 2048 + k * 1024); } while (0)
; #define PG8_LDB(dst, b, h) do { _Pragma("unroll") for (int n = 0; n < 2; ++n) _Pragma("unroll") for (int k = 0; k < 2; ++k) dst[n][k] = *(const LAS bf16x8*)(lds + PG8_SB(b, h) + boff + n * 2048 + k * 1024); } while (0)
; #define PG8_MMA(ai, bj, At, Bt) do { __builtin_amdgcn_s_setprio(1); _Pragma("unroll") for (int m = 0; m < 4; ++m) _Pragma("unroll") for (int n = 0; n < 2; ++n) _Pragma("unroll") for (int k = 0; k < 2; ++k) \
;         acc[ai][bj][m][n] = __builtin_amdgcn_mfma_f32_16x16x32_bf16(Bt[n][k], At[m][k], acc[ai][bj][m][n], 0, 0, 0); __builtin_amdgcn_s_setprio(0); } while (0)
; #define PG8_WAIT_V(n) asm volatile("s_waitcnt vmcnt(" #n ")" ::: "memory")
; #define PG8_BAR __builtin_amdgcn_s_barrier()
; template <class Epi, class Sched>
; __device__ __forceinline__ void gemm_phase(LAS unsigned char* lds, const Gemm g, const Sched& S, const Epi& E) {
;     ...
;         for (int t = 0; t < nt; t += 2) {
;             const bool last = (t == nt - 2);
;             const char* a1 = cA + (size_t)(t + 1) * kstep;
;             const char* a2 = last ? nA : cA + (size_t)(t + 2) * kstep; const char* b2 = last ? nB : cB + (size_t)(t + 2) * kstep;
;             const char* a3 = a2 + kstep; const char* b3 = b2 + kstep;
;             if (last && has_next) S.a_ready(nxt);
;             PG8_LDB(B0, 0, 0); PG8_SCHED; PG8_LDA(At, 0, 0); PG8_STAGE(PG8_SA(1, 1), a1 + hstep, voffA);
;             PG8_WAIT_L(8); PG8_BAR; PG8_WAIT_L(0); PG8_MMA(0, 0, At, B0); PG8_BAR; PG8_SCHED;
;             PG8_LDB(B1, 0, 1); PG8_STAGE(PG8_SB(0, 0), b2, voffB);
;             PG8_BAR; PG8_WAIT_L(0); PG8_MMA(0, 1, At, B1); PG8_BAR;
;             PG8_LDA(At, 0, 1); PG8_STAGE(PG8_SA(0, 0), a2, voffA);
;             PG8_BAR; PG8_WAIT_L(0); PG8_MMA(1, 0, At, B0); PG8_BAR; PG8_SCHED;
;             PG8_STAGE(PG8_SB(0, 1), b2 + hstep, voffB);
;             PG8_WAIT_V(6); PG8_BAR; PG8_MMA(1, 1, At, B1); PG8_BAR;
.LBB0_1343:
	s_nop 0
	v_add_u32_e32 v136, s42, v139
	ds_read_b128 v[142:145], v136
	ds_read_b128 v[146:149], v136 offset:1024
	ds_read_b128 v[150:153], v136 offset:2048
	ds_read_b128 v[154:157], v136 offset:3072
	s_add_u32 s18, s16, 0x100
	s_addc_u32 s19, s17, 0
	s_cmpk_eq_i32 s40, 0x7c
	s_cselect_b32 s23, s3, s19
	s_cselect_b32 s22, s7, s18
	s_cselect_b32 s21, s5, s39
	s_cselect_b32 s20, s37, s38
	v_lshl_add_u64 v[136:137], s[16:17], 0, v[132:133]
	s_add_i32 m0, s13, 0xc000
	ds_read_b128 v[158:161], v141
	ds_read_b128 v[162:165], v141 offset:1024
	ds_read_b128 v[166:169], v141 offset:2048
	ds_read_b128 v[170:173], v141 offset:3072
	ds_read_b128 v[174:177], v141 offset:4096
	ds_read_b128 v[178:181], v141 offset:5120
	ds_read_b128 v[182:185], v141 offset:6144
	ds_read_b128 v[186:189], v141 offset:7168
	global_load_lds_dwordx4 v[136:137], off
	v_lshl_add_u64 v[136:137], s[16:17], 0, v[134:135]
	s_add_i32 m0, s13, 0xe000
	s_nop 0
	global_load_lds_dwordx4 v[136:137], off
	s_waitcnt lgkmcnt(8)
	s_barrier
	s_waitcnt lgkmcnt(0)
	s_waitcnt lgkmcnt(0)
	v_mfma_f32_16x16x32_bf16 v[126:129], v[142:145], v[158:161], v[126:129]
	v_mfma_f32_16x16x32_bf16 v[122:125], v[150:153], v[158:161], v[122:125]
	v_mfma_f32_16x16x32_bf16 v[110:113], v[142:145], v[166:169], v[110:113]
	v_mfma_f32_16x16x32_bf16 v[106:109], v[150:153], v[166:169], v[106:109]
	v_mfma_f32_16x16x32_bf16 v[94:97], v[142:145], v[174:177], v[94:97]
	v_mfma_f32_16x16x32_bf16 v[90:93], v[150:153], v[174:177], v[90:93]
	v_mfma_f32_16x16x32_bf16 v[78:81], v[142:145], v[182:185], v[78:81]
	v_mfma_f32_16x16x32_bf16 v[74:77], v[150:153], v[182:185], v[74:77]
	v_mfma_f32_16x16x32_bf16 v[126:129], v[146:149], v[162:165], v[126:129]
	v_mfma_f32_16x16x32_bf16 v[122:125], v[154:157], v[162:165], v[122:125]
	v_mfma_f32_16x16x32_bf16 v[110:113], v[146:149], v[170:173], v[110:113]
	v_mfma_f32_16x16x32_bf16 v[106:109], v[154:157], v[170:173], v[106:109]
	v_mfma_f32_16x16x32_bf16 v[94:97], v[146:149], v[178:181], v[94:97]
	v_mfma_f32_16x16x32_bf16 v[90:93], v[154:157], v[178:181], v[90:93]
	v_mfma_f32_16x16x32_bf16 v[78:81], v[146:149], v[186:189], v[78:81]
	v_mfma_f32_16x16x32_bf16 v[74:77], v[154:157], v[186:189], v[74:77]
	s_barrier
	s_add_i32 s41, 0, 0x14000
	v_add_u32_e32 v136, s41, v139
	s_add_i32 s16, s42, s28
	ds_read_b128 v[190:193], v136
	ds_read_b128 v[194:197], v136 offset:1024
	ds_read_b128 v[198:201], v136 offset:2048
	ds_read_b128 v[202:205], v136 offset:3072
	v_lshl_add_u64 v[136:137], s[20:21], 0, v[0:1]
	s_mov_b32 m0, s16
	v_lshl_add_u64 v[206:207], s[20:21], 0, v[130:131]
	global_load_lds_dwordx4 v[136:137], off
	s_add_i32 m0, s16, 0x2000
	s_nop 0
	global_load_lds_dwordx4 v[206:207], off
	s_barrier
	s_waitcnt lgkmcnt(0)
	s_waitcnt lgkmcnt(0)
	v_mfma_f32_16x16x32_bf16 v[118:121], v[190:193], v[158:161], v[118:121]
	v_mfma_f32_16x16x32_bf16 v[114:117], v[198:201], v[158:161], v[114:117]
	v_mfma_f32_16x16x32_bf16 v[102:105], v[190:193], v[166:169], v[102:105]
	v_mfma_f32_16x16x32_bf16 v[98:101], v[198:201], v[166:169], v[98:101]
	v_mfma_f32_16x16x32_bf16 v[86:89], v[190:193], v[174:177], v[86:89]
	v_mfma_f32_16x16x32_bf16 v[82:85], v[198:201], v[174:177], v[82:85]
	v_mfma_f32_16x16x32_bf16 v[70:73], v[190:193], v[182:185], v[70:73]
	v_mfma_f32_16x16x32_bf16 v[66:69], v[198:201], v[182:185], v[66:69]
	v_mfma_f32_16x16x32_bf16 v[118:121], v[194:197], v[162:165], v[118:121]
	v_mfma_f32_16x16x32_bf16 v[114:117], v[202:205], v[162:165], v[114:117]
	v_mfma_f32_16x16x32_bf16 v[102:105], v[194:197], v[170:173], v[102:105]
	v_mfma_f32_16x16x32_bf16 v[98:101], v[202:205], v[170:173], v[98:101]
	v_mfma_f32_16x16x32_bf16 v[86:89], v[194:197], v[178:181], v[86:89]
	v_mfma_f32_16x16x32_bf16 v[82:85], v[202:205], v[178:181], v[82:85]
	v_mfma_f32_16x16x32_bf16 v[70:73], v[194:197], v[186:189], v[70:73]
	v_mfma_f32_16x16x32_bf16 v[66:69], v[202:205], v[186:189], v[66:69]
	s_mov_b32 m0, s13
	v_lshl_add_u64 v[208:209], s[22:23], 0, v[0:1]
	s_barrier
	ds_read_b128 v[158:161], v141 offset:16384
	ds_read_b128 v[162:165], v141 offset:17408
	ds_read_b128 v[166:169], v141 offset:18432
	ds_read_b128 v[170:173], v141 offset:19456
	ds_read_b128 v[174:177], v141 offset:20480
	ds_read_b128 v[178:181], v141 offset:21504
	ds_read_b128 v[182:185], v141 offset:22528
	ds_read_b128 v[186:189], v141 offset:23552
	global_load_lds_dwordx4 v[208:209], off
	v_lshl_add_u64 v[210:211], s[22:23], 0, v[130:131]
	s_mov_b32 m0, s15
	s_nop 0
	global_load_lds_dwordx4 v[210:211], off
	s_barrier
	s_waitcnt lgkmcnt(0)
	s_waitcnt lgkmcnt(0)
	v_mfma_f32_16x16x32_bf16 v[62:65], v[142:145], v[158:161], v[62:65]
	v_mfma_f32_16x16x32_bf16 v[58:61], v[150:153], v[158:161], v[58:61]
	v_mfma_f32_16x16x32_bf16 v[46:49], v[142:145], v[166:169], v[46:49]
	v_mfma_f32_16x16x32_bf16 v[42:45], v[150:153], v[166:169], v[42:45]
	v_mfma_f32_16x16x32_bf16 v[30:33], v[142:145], v[174:177], v[30:33]
	v_mfma_f32_16x16x32_bf16 v[26:29], v[150:153], v[174:177], v[26:29]
	v_mfma_f32_16x16x32_bf16 v[14:17], v[142:145], v[182:185], v[14:17]
	v_mfma_f32_16x16x32_bf16 v[10:13], v[150:153], v[182:185], v[10:13]
	v_mfma_f32_16x16x32_bf16 v[62:65], v[146:149], v[162:165], v[62:65]
	v_mfma_f32_16x16x32_bf16 v[58:61], v[154:157], v[162:165], v[58:61]
	v_mfma_f32_16x16x32_bf16 v[46:49], v[146:149], v[170:173], v[46:49]
	v_mfma_f32_16x16x32_bf16 v[42:45], v[154:157], v[170:173], v[42:45]
	v_mfma_f32_16x16x32_bf16 v[30:33], v[146:149], v[178:181], v[30:33]
	v_mfma_f32_16x16x32_bf16 v[26:29], v[154:157], v[178:181], v[26:29]
	v_mfma_f32_16x16x32_bf16 v[14:17], v[146:149], v[186:189], v[14:17]
	v_mfma_f32_16x16x32_bf16 v[10:13], v[154:157], v[186:189], v[10:13]
	s_barrier
; #define PG8_STAGE(bufoff, gbase, voff) do { _Pragma("unroll") for (int _i = 0; _i < 2; ++_i) \
;         __builtin_amdgcn_global_load_lds((const unsigned*)((const char*)(gbase) + (voff)[_i]), (LAS unsigned*)(lds + (bufoff) + ldsw + _i * 8192), 16, 0, 0); } while (0)
; #define PG8_LDA(dst, b, h) do { _Pragma("unroll") for (int m = 0; m < 4; ++m) _Pragma("unroll") for (int k = 0; k < 2; ++k) dst[m][k] = *(const LAS bf16x8*)(lds + PG8_SA(b, h) + aoff + m * 2048 + k * 1024); } while (0)
; #define PG8_LDB(dst, b, h) do { _Pragma("unroll") for (int n = 0; n < 2; ++n) _Pragma("unroll") for (int k = 0; k < 2; ++k) dst[n][k] = *(const LAS bf16x8*)(lds + PG8_SB(b, h) + boff + n * 2048 + k * 1024); } while (0)
; #define PG8_MMA(ai, bj, At, Bt) do { __builtin_amdgcn_s_setprio(1); _Pragma("unroll") for (int m = 0; m < 4; ++m) _Pragma("unroll") for (int n = 0; n < 2; ++n) _Pragma("unroll") for (int k = 0; k < 2; ++k) \
;         acc[ai][bj][m][n] = __builtin_amdgcn_mfma_f32_16x16x32_bf16(Bt[n][k], At[m][k], acc[ai][bj][m][n], 0, 0, 0); __builtin_amdgcn_s_setprio(0); } while (0)
; #define PG8_WAIT_V(n) asm volatile("s_waitcnt vmcnt(" #n ")" ::: "memory")
; #define PG8_WAIT_L(n) asm volatile("s_waitcnt lgkmcnt(" #n ")" ::: "memory")
; #define PG8_BAR __builtin_amdgcn_s_barrier()
; #define PG8_SCHED __builtin_amdgcn_sched_barrier(0)
; template <class Epi, class Sched>
; __device__ __forceinline__ void gemm_phase(LAS unsigned char* lds, const Gemm g, const Sched& S, const Epi& E) {
;     ...
;             PG8_BAR; PG8_WAIT_L(0); PG8_MMA(1, 0, At, B0); PG8_BAR; PG8_SCHED;
;             PG8_STAGE(PG8_SB(0, 1), b2 + hstep, voffB);
;             PG8_WAIT_V(6); PG8_BAR; PG8_MMA(1, 1, At, B1); PG8_BAR;
;             PG8_LDB(B0, 1, 0); PG8_SCHED; PG8_LDA(At, 1, 0); PG8_STAGE(PG8_SA(0, 1), a2 + hstep, voffA);
;             PG8_WAIT_L(8); PG8_BAR; PG8_WAIT_L(0); PG8_MMA(0, 0, At, B0); PG8_BAR; PG8_SCHED;
;             PG8_LDB(B1, 1, 1); PG8_STAGE(PG8_SB(1, 0), b3, voffB);
;             PG8_BAR; PG8_WAIT_L(0); PG8_MMA(0, 1, At, B1); PG8_BAR;
;             PG8_LDA(At, 1, 1); PG8_STAGE(PG8_SA(1, 0), a3, voffA);
;             PG8_BAR; PG8_WAIT_L(0); PG8_MMA(1, 0, At, B0); PG8_BAR; PG8_SCHED;
	s_add_u32 s16, s20, 0x200000
	s_addc_u32 s17, s21, 0
	s_add_i32 s41, s41, s28
	v_lshl_add_u64 v[142:143], s[16:17], 0, v[0:1]
	s_mov_b32 m0, s41
	s_nop 0
	global_load_lds_dwordx4 v[142:143], off
	v_lshl_add_u64 v[142:143], s[16:17], 0, v[130:131]
	s_add_i32 m0, s41, 0x2000
	s_nop 0
	global_load_lds_dwordx4 v[142:143], off
	s_waitcnt vmcnt(6)
	s_barrier
	v_mfma_f32_16x16x32_bf16 v[54:57], v[190:193], v[158:161], v[54:57]
	v_mfma_f32_16x16x32_bf16 v[50:53], v[198:201], v[158:161], v[50:53]
	v_mfma_f32_16x16x32_bf16 v[38:41], v[190:193], v[166:169], v[38:41]
	v_mfma_f32_16x16x32_bf16 v[34:37], v[198:201], v[166:169], v[34:37]
	v_mfma_f32_16x16x32_bf16 v[22:25], v[190:193], v[174:177], v[22:25]
	v_mfma_f32_16x16x32_bf16 v[18:21], v[198:201], v[174:177], v[18:21]
	v_mfma_f32_16x16x32_bf16 v[6:9], v[190:193], v[182:185], v[6:9]
	v_mfma_f32_16x16x32_bf16 v[2:5], v[198:201], v[182:185], v[2:5]
	v_mfma_f32_16x16x32_bf16 v[54:57], v[194:197], v[162:165], v[54:57]
	v_mfma_f32_16x16x32_bf16 v[50:53], v[202:205], v[162:165], v[50:53]
	v_mfma_f32_16x16x32_bf16 v[38:41], v[194:197], v[170:173], v[38:41]
	v_mfma_f32_16x16x32_bf16 v[34:37], v[202:205], v[170:173], v[34:37]
	v_mfma_f32_16x16x32_bf16 v[22:25], v[194:197], v[178:181], v[22:25]
	v_mfma_f32_16x16x32_bf16 v[18:21], v[202:205], v[178:181], v[18:21]
	v_mfma_f32_16x16x32_bf16 v[6:9], v[194:197], v[186:189], v[6:9]
	v_mfma_f32_16x16x32_bf16 v[2:5], v[202:205], v[186:189], v[2:5]
	s_add_i32 s41, 0, 0x18000
	v_add_u32_e32 v154, s41, v139
	s_barrier
	ds_read_b128 v[142:145], v154
	ds_read_b128 v[146:149], v154 offset:1024
	ds_read_b128 v[150:153], v154 offset:2048
	ds_read_b128 v[154:157], v154 offset:3072
	s_add_u32 s16, s22, 0x200000
	s_addc_u32 s17, s23, 0
	s_mov_b32 m0, s29
	v_lshl_add_u64 v[190:191], s[16:17], 0, v[0:1]
	ds_read_b128 v[158:161], v141 offset:32768
	ds_read_b128 v[162:165], v141 offset:33792
	ds_read_b128 v[166:169], v141 offset:34816
	ds_read_b128 v[170:173], v141 offset:35840
	ds_read_b128 v[174:177], v141 offset:36864
	ds_read_b128 v[178:181], v141 offset:37888
	ds_read_b128 v[182:185], v141 offset:38912
	ds_read_b128 v[186:189], v141 offset:39936
	global_load_lds_dwordx4 v[190:191], off
	v_lshl_add_u64 v[190:191], s[16:17], 0, v[130:131]
	s_mov_b32 m0, s30
	s_nop 0
	global_load_lds_dwordx4 v[190:191], off
	s_waitcnt lgkmcnt(8)
	s_barrier
	s_waitcnt lgkmcnt(0)
	s_waitcnt lgkmcnt(0)
	v_mfma_f32_16x16x32_bf16 v[126:129], v[142:145], v[158:161], v[126:129]
	v_mfma_f32_16x16x32_bf16 v[122:125], v[150:153], v[158:161], v[122:125]
	v_mfma_f32_16x16x32_bf16 v[110:113], v[142:145], v[166:169], v[110:113]
	v_mfma_f32_16x16x32_bf16 v[106:109], v[150:153], v[166:169], v[106:109]
	v_mfma_f32_16x16x32_bf16 v[94:97], v[142:145], v[174:177], v[94:97]
	v_mfma_f32_16x16x32_bf16 v[90:93], v[150:153], v[174:177], v[90:93]
	v_mfma_f32_16x16x32_bf16 v[78:81], v[142:145], v[182:185], v[78:81]
	v_mfma_f32_16x16x32_bf16 v[74:77], v[150:153], v[182:185], v[74:77]
	v_mfma_f32_16x16x32_bf16 v[126:129], v[146:149], v[162:165], v[126:129]
	v_mfma_f32_16x16x32_bf16 v[122:125], v[154:157], v[162:165], v[122:125]
	v_mfma_f32_16x16x32_bf16 v[110:113], v[146:149], v[170:173], v[110:113]
	v_mfma_f32_16x16x32_bf16 v[106:109], v[154:157], v[170:173], v[106:109]
	v_mfma_f32_16x16x32_bf16 v[94:97], v[146:149], v[178:181], v[94:97]
	v_mfma_f32_16x16x32_bf16 v[90:93], v[154:157], v[178:181], v[90:93]
	v_mfma_f32_16x16x32_bf16 v[78:81], v[146:149], v[186:189], v[78:81]
	v_mfma_f32_16x16x32_bf16 v[74:77], v[154:157], v[186:189], v[74:77]
	s_barrier
	s_add_i32 s22, 0, 0x1c000
	s_add_i32 s16, s41, s28
	v_add_u32_e32 v202, s22, v139
	v_lshl_add_u64 v[136:137], v[136:137], 0, s[44:45]
	s_mov_b32 m0, s16
	ds_read_b128 v[190:193], v202
	ds_read_b128 v[194:197], v202 offset:1024
	ds_read_b128 v[198:201], v202 offset:2048
	ds_read_b128 v[202:205], v202 offset:3072
	global_load_lds_dwordx4 v[136:137], off
	v_lshl_add_u64 v[136:137], v[206:207], 0, s[44:45]
	s_add_i32 m0, s16, 0x2000
	s_nop 0
	global_load_lds_dwordx4 v[136:137], off
	s_barrier
	s_waitcnt lgkmcnt(0)
	s_waitcnt lgkmcnt(0)
	v_mfma_f32_16x16x32_bf16 v[118:121], v[190:193], v[158:161], v[118:121]
	v_mfma_f32_16x16x32_bf16 v[114:117], v[198:201], v[158:161], v[114:117]
	v_mfma_f32_16x16x32_bf16 v[102:105], v[190:193], v[166:169], v[102:105]
	v_mfma_f32_16x16x32_bf16 v[98:101], v[198:201], v[166:169], v[98:101]
	v_mfma_f32_16x16x32_bf16 v[86:89], v[190:193], v[174:177], v[86:89]
	v_mfma_f32_16x16x32_bf16 v[82:85], v[198:201], v[174:177], v[82:85]
	v_mfma_f32_16x16x32_bf16 v[70:73], v[190:193], v[182:185], v[70:73]
	v_mfma_f32_16x16x32_bf16 v[66:69], v[198:201], v[182:185], v[66:69]
	v_mfma_f32_16x16x32_bf16 v[118:121], v[194:197], v[162:165], v[118:121]
	v_mfma_f32_16x16x32_bf16 v[114:117], v[202:205], v[162:165], v[114:117]
	v_mfma_f32_16x16x32_bf16 v[102:105], v[194:197], v[170:173], v[102:105]
	v_mfma_f32_16x16x32_bf16 v[98:101], v[202:205], v[170:173], v[98:101]
	v_mfma_f32_16x16x32_bf16 v[86:89], v[194:197], v[178:181], v[86:89]
	v_mfma_f32_16x16x32_bf16 v[82:85], v[202:205], v[178:181], v[82:85]
	v_mfma_f32_16x16x32_bf16 v[70:73], v[194:197], v[186:189], v[70:73]
	v_mfma_f32_16x16x32_bf16 v[66:69], v[202:205], v[186:189], v[66:69]
	s_mov_b32 m0, s34
	v_lshl_add_u64 v[136:137], v[208:209], 0, s[44:45]
	s_barrier
; #define PG8_STAGE(bufoff, gbase, voff) do { _Pragma("unroll") for (int _i = 0; _i < 2; ++_i) \
;         __builtin_amdgcn_global_load_lds((const unsigned*)((const char*)(gbase) + (voff)[_i]), (LAS unsigned*)(lds + (bufoff) + ldsw + _i * 8192), 16, 0, 0); } while (0)
; #define PG8_MMA(ai, bj, At, Bt) do { __builtin_amdgcn_s_setprio(1); _Pragma("unroll") for (int m = 0; m < 4; ++m) _Pragma("unroll") for (int n = 0; n < 2; ++n) _Pragma("unroll") for (int k = 0; k < 2; ++k) \
;         acc[ai][bj][m][n] = __builtin_amdgcn_mfma_f32_16x16x32_bf16(Bt[n][k], At[m][k], acc[ai][bj][m][n], 0, 0, 0); __builtin_amdgcn_s_setprio(0); } while (0)
; #define PG8_WAIT_V(n) asm volatile("s_waitcnt vmcnt(" #n ")" ::: "memory")
; #define PG8_WAIT_L(n) asm volatile("s_waitcnt lgkmcnt(" #n ")" ::: "memory")
; #define PG8_BAR __builtin_amdgcn_s_barrier()
; #define PG8_SCHED __builtin_amdgcn_sched_barrier(0)
; template <class Epi, class Sched>
; __device__ __forceinline__ void gemm_phase(LAS unsigned char* lds, const Gemm g, const Sched& S, const Epi& E) {
;     ...
;             PG8_BAR; PG8_WAIT_L(0); PG8_MMA(1, 0, At, B0); PG8_BAR; PG8_SCHED;
;             PG8_STAGE(PG8_SB(1, 1), b3 + hstep, voffB);
;             PG8_WAIT_V(6); PG8_BAR; PG8_MMA(1, 1, At, B1); PG8_BAR;
;         }
;         E(acc, cur, wr, wc, fr, fq); S.done(cur);
;     __device__ __forceinline__ void operator()(const f32x4 (&acc)[2][2][4][2], const pg8::Unit& u, int wr, int wc, int fr, int fq) const {
;         const int row0 = u.pm * 256 + wr * 64 + fr; const int col0 = u.pn * 256 + wc * 32 + 4 * fq;
; #pragma unroll
;         for (int ai = 0; ai < 2; ++ai)
; #pragma unroll
;             for (int m = 0; m < 4; ++m) { const int row = row0 + ai * 128 + m * 16;
;                 const float* ip; float* op; int b;
;                 if (row < ML_ROWS) { b = row >> 11; ip = xi + (size_t)row * D; op = xo + (size_t)row * D; }
;                 else { b = 8; ip = ci + (size_t)(row - ML_ROWS) * D; op = co + (size_t)(row - ML_ROWS) * D; }
;                 const float* gp = mod + (size_t)b * 12288 + slot * 2048;
	ds_read_b128 v[158:161], v141 offset:49152
	ds_read_b128 v[162:165], v141 offset:50176
	ds_read_b128 v[166:169], v141 offset:51200
	ds_read_b128 v[170:173], v141 offset:52224
	ds_read_b128 v[174:177], v141 offset:53248
	ds_read_b128 v[178:181], v141 offset:54272
	ds_read_b128 v[182:185], v141 offset:55296
	ds_read_b128 v[186:189], v141 offset:56320
	global_load_lds_dwordx4 v[136:137], off
	v_lshl_add_u64 v[136:137], v[210:211], 0, s[44:45]
	s_mov_b32 m0, s35
	s_nop 0
	global_load_lds_dwordx4 v[136:137], off
	s_barrier
	s_waitcnt lgkmcnt(0)
	s_waitcnt lgkmcnt(0)
	v_mfma_f32_16x16x32_bf16 v[62:65], v[142:145], v[158:161], v[62:65]
	v_mfma_f32_16x16x32_bf16 v[58:61], v[150:153], v[158:161], v[58:61]
	v_mfma_f32_16x16x32_bf16 v[46:49], v[142:145], v[166:169], v[46:49]
	v_mfma_f32_16x16x32_bf16 v[42:45], v[150:153], v[166:169], v[42:45]
	v_mfma_f32_16x16x32_bf16 v[30:33], v[142:145], v[174:177], v[30:33]
	v_mfma_f32_16x16x32_bf16 v[26:29], v[150:153], v[174:177], v[26:29]
	v_mfma_f32_16x16x32_bf16 v[14:17], v[142:145], v[182:185], v[14:17]
	v_mfma_f32_16x16x32_bf16 v[10:13], v[150:153], v[182:185], v[10:13]
	v_mfma_f32_16x16x32_bf16 v[62:65], v[146:149], v[162:165], v[62:65]
	v_mfma_f32_16x16x32_bf16 v[58:61], v[154:157], v[162:165], v[58:61]
	v_mfma_f32_16x16x32_bf16 v[46:49], v[146:149], v[170:173], v[46:49]
	v_mfma_f32_16x16x32_bf16 v[42:45], v[154:157], v[170:173], v[42:45]
	v_mfma_f32_16x16x32_bf16 v[30:33], v[146:149], v[178:181], v[30:33]
	v_mfma_f32_16x16x32_bf16 v[26:29], v[154:157], v[178:181], v[26:29]
	v_mfma_f32_16x16x32_bf16 v[14:17], v[146:149], v[186:189], v[14:17]
	v_mfma_f32_16x16x32_bf16 v[10:13], v[154:157], v[186:189], v[10:13]
	s_barrier
	s_add_u32 s16, s20, 0x200080
	s_addc_u32 s17, s21, 0
	s_add_i32 s20, s22, s28
	v_lshl_add_u64 v[136:137], s[16:17], 0, v[0:1]
	s_mov_b32 m0, s20
	s_nop 0
	global_load_lds_dwordx4 v[136:137], off
	v_lshl_add_u64 v[136:137], s[16:17], 0, v[130:131]
	s_add_i32 m0, s20, 0x2000
	s_nop 0
	global_load_lds_dwordx4 v[136:137], off
	s_waitcnt vmcnt(6)
	s_barrier
	v_mfma_f32_16x16x32_bf16 v[54:57], v[190:193], v[158:161], v[54:57]
	v_mfma_f32_16x16x32_bf16 v[50:53], v[198:201], v[158:161], v[50:53]
	v_mfma_f32_16x16x32_bf16 v[38:41], v[190:193], v[166:169], v[38:41]
	v_mfma_f32_16x16x32_bf16 v[34:37], v[198:201], v[166:169], v[34:37]
	v_mfma_f32_16x16x32_bf16 v[22:25], v[190:193], v[174:177], v[22:25]
	v_mfma_f32_16x16x32_bf16 v[18:21], v[198:201], v[174:177], v[18:21]
	v_mfma_f32_16x16x32_bf16 v[6:9], v[190:193], v[182:185], v[6:9]
	v_mfma_f32_16x16x32_bf16 v[2:5], v[198:201], v[182:185], v[2:5]
	v_mfma_f32_16x16x32_bf16 v[54:57], v[194:197], v[162:165], v[54:57]
	v_mfma_f32_16x16x32_bf16 v[50:53], v[202:205], v[162:165], v[50:53]
	v_mfma_f32_16x16x32_bf16 v[38:41], v[194:197], v[170:173], v[38:41]
	v_mfma_f32_16x16x32_bf16 v[34:37], v[202:205], v[170:173], v[34:37]
	v_mfma_f32_16x16x32_bf16 v[22:25], v[194:197], v[178:181], v[22:25]
	v_mfma_f32_16x16x32_bf16 v[18:21], v[202:205], v[178:181], v[18:21]
	v_mfma_f32_16x16x32_bf16 v[6:9], v[194:197], v[186:189], v[6:9]
	v_mfma_f32_16x16x32_bf16 v[2:5], v[202:205], v[186:189], v[2:5]
	s_add_i32 s40, s40, 2
	s_add_u32 s38, s38, 0x100
	s_addc_u32 s39, s39, 0
	s_cmpk_gt_u32 s40, 0x7d
	s_mov_b64 s[16:17], s[18:19]
	s_barrier
	s_cbranch_scc0 .LBB0_1343
	s_lshl_b32 s3, s14, 8
	s_add_i32 s3, s3, s31
	v_readlane_b32 s40, v251, 0
	v_readlane_b32 s41, v251, 1
	v_readlane_b32 s42, v251, 2
	v_readlane_b32 s43, v251, 3
	v_readlane_b32 s44, v251, 4
	v_readlane_b32 s45, v251, 5
	v_readlane_b32 s46, v251, 6
	v_readlane_b32 s47, v251, 7
	v_readlane_b32 s18, v254, 2
	v_readlane_b32 s19, v254, 3
	s_add_i32 s5, s3, 0xffffc000
	s_ashr_i32 s7, s3, 11
	s_cmpk_lt_i32 s3, 0x4000
	s_cselect_b32 s20, s42, s60
	s_cselect_b32 s21, s43, s61
	s_cselect_b32 s5, s3, s5
	s_cselect_b32 s7, s7, 8
	s_mul_i32 s7, s7, 0xc000
	s_add_u32 s18, s18, s7
	s_addc_u32 s19, s19, 0
	s_add_u32 s18, s18, 0xa000
	s_addc_u32 s19, s19, 0
	v_add_u32_e32 v136, s5, v138
	v_lshl_or_b32 v137, s12, 8, v140
	v_lshlrev_b32_e32 v137, 2, v137
	v_lshl_or_b32 v136, v136, 13, v137
	s_mov_b32 s12, s4
	s_mov_b32 s14, s6
	s_cmp_lg_u32 s36, 3
	s_cbranch_scc1 .Lsk_normal
	v_readlane_b32 s5, v253, 24
	s_cmpk_lg_u32 s46, 0x100
	s_cbranch_scc1 .Lsk_normal
	s_cmpk_lg_u32 s5, 0x240
	s_cbranch_scc1 .Lsk_normal
	s_and_b32 s7, s54, 3
	s_lshr_b32 s5, s54, 2
	s_lshr_b32 s3, s24, 6
	s_lshl_b32 s23, s5, 3
	s_add_i32 s23, s23, s3
	s_lshl_b32 s23, s23, 2
	v_readlane_b32 s38, v251, 10
	v_readlane_b32 s39, v251, 11
	s_add_u32 s38, s38, s23
	s_addc_u32 s39, s39, 0
	s_add_u32 s38, s38, 0x3700
	s_addc_u32 s39, s39, 0
	v_readlane_b32 s16, v251, 4
	v_readlane_b32 s17, v251, 5
	s_lshl_b32 s5, s5, 20
	s_add_u32 s16, s16, 0x24000000
	s_addc_u32 s17, s17, 0
	s_add_u32 s16, s16, s5
	s_addc_u32 s17, s17, 0
	v_add_u32_e32 v142, s31, v138
	v_lshlrev_b32_e32 v143, 2, v140
	v_lshl_or_b32 v142, v142, 10, v143
	global_load_dwordx4 v[146:149], v137, s[18:19]
	global_load_dwordx4 v[150:153], v137, s[18:19] offset:64
	global_load_dwordx4 v[154:157], v137, s[18:19] offset:512
	global_load_dwordx4 v[158:161], v137, s[18:19] offset:576
	s_cmp_eq_u32 s7, 1
	s_cbranch_scc1 .Lsk_v1
	s_cmp_eq_u32 s7, 2
	s_cbranch_scc1 .Lsk_v2
	s_cmp_eq_u32 s7, 3
	s_cbranch_scc1 .Lsk_v3
